# stacked: hand-written P8 halo hook + 32-MFMA joint schedule (chains adjacent, grouped by B fragment) + K-loop setprio removed
# speedup vs baseline: 1.0604x; 1.0051x over previous
.LBB0_124:
	ds_read_b128 v[138:141], v151
	ds_read_b128 v[142:145], v151 offset:1024
	ds_read_b128 v[158:161], v151 offset:2048
	ds_read_b128 v[162:165], v151 offset:3072
	ds_read_b128 v[166:169], v152
	ds_read_b128 v[170:173], v152 offset:1024
	ds_read_b128 v[174:177], v152 offset:2048
	ds_read_b128 v[178:181], v152 offset:3072
	s_add_i32 s47, s9, s10
	s_add_i32 s75, s47, 0x100
	s_add_i32 s13, s9, s11
	s_cmp_eq_u32 s9, s12
	s_cselect_b32 s13, s7, s13
	s_cselect_b32 s80, s6, s75
	s_add_i32 s75, s47, 0x80
	s_mov_b32 m0, s58
	ds_read_b128 v[182:185], v153
	ds_read_b128 v[186:189], v153 offset:1024
	buffer_load_dwordx4 v1, s[28:31], s75 offen lds
	s_mov_b32 m0, s59
	ds_read_b128 v[190:193], v153 offset:2048
	ds_read_b128 v[194:197], v153 offset:3072
	buffer_load_dwordx4 v147, s[28:31], s75 offen lds
	s_add_i32 s47, s47, 0x80080
	s_mov_b32 m0, s70
	ds_read_b128 v[198:201], v153 offset:4096
	ds_read_b128 v[202:205], v153 offset:5120
	buffer_load_dwordx4 v1, s[28:31], s47 offen lds
	s_mov_b32 m0, s71
	ds_read_b128 v[206:209], v153 offset:6144
	ds_read_b128 v[210:213], v153 offset:7168
	buffer_load_dwordx4 v147, s[28:31], s47 offen lds
	s_waitcnt vmcnt(8)
	s_waitcnt lgkmcnt(0)
	s_barrier
	s_waitcnt lgkmcnt(0)
	v_mfma_f32_16x16x32_bf16 v[130:133], v[138:141], v[182:185], v[130:133]
	v_mfma_f32_16x16x32_bf16 v[130:133], v[142:145], v[186:189], v[130:133]
	v_mfma_f32_16x16x32_bf16 v[114:117], v[138:141], v[190:193], v[114:117]
	v_mfma_f32_16x16x32_bf16 v[114:117], v[142:145], v[194:197], v[114:117]
	v_mfma_f32_16x16x32_bf16 v[98:101], v[138:141], v[198:201], v[98:101]
	v_mfma_f32_16x16x32_bf16 v[98:101], v[142:145], v[202:205], v[98:101]
	v_mfma_f32_16x16x32_bf16 v[82:85], v[138:141], v[206:209], v[82:85]
	v_mfma_f32_16x16x32_bf16 v[82:85], v[142:145], v[210:213], v[82:85]
	v_mfma_f32_16x16x32_bf16 v[126:129], v[158:161], v[182:185], v[126:129]
	v_mfma_f32_16x16x32_bf16 v[126:129], v[162:165], v[186:189], v[126:129]
	v_mfma_f32_16x16x32_bf16 v[110:113], v[158:161], v[190:193], v[110:113]
	v_mfma_f32_16x16x32_bf16 v[110:113], v[162:165], v[194:197], v[110:113]
	v_mfma_f32_16x16x32_bf16 v[94:97], v[158:161], v[198:201], v[94:97]
	v_mfma_f32_16x16x32_bf16 v[94:97], v[162:165], v[202:205], v[94:97]
	v_mfma_f32_16x16x32_bf16 v[78:81], v[158:161], v[206:209], v[78:81]
	v_mfma_f32_16x16x32_bf16 v[78:81], v[162:165], v[210:213], v[78:81]
	v_mfma_f32_16x16x32_bf16 v[122:125], v[166:169], v[182:185], v[122:125]
	v_mfma_f32_16x16x32_bf16 v[122:125], v[170:173], v[186:189], v[122:125]
	v_mfma_f32_16x16x32_bf16 v[106:109], v[166:169], v[190:193], v[106:109]
	v_mfma_f32_16x16x32_bf16 v[106:109], v[170:173], v[194:197], v[106:109]
	v_mfma_f32_16x16x32_bf16 v[90:93], v[166:169], v[198:201], v[90:93]
	v_mfma_f32_16x16x32_bf16 v[90:93], v[170:173], v[202:205], v[90:93]
	v_mfma_f32_16x16x32_bf16 v[74:77], v[166:169], v[206:209], v[74:77]
	v_mfma_f32_16x16x32_bf16 v[74:77], v[170:173], v[210:213], v[74:77]
	v_mfma_f32_16x16x32_bf16 v[118:121], v[174:177], v[182:185], v[118:121]
	v_mfma_f32_16x16x32_bf16 v[118:121], v[178:181], v[186:189], v[118:121]
	v_mfma_f32_16x16x32_bf16 v[102:105], v[174:177], v[190:193], v[102:105]
	v_mfma_f32_16x16x32_bf16 v[102:105], v[178:181], v[194:197], v[102:105]
	v_mfma_f32_16x16x32_bf16 v[86:89], v[174:177], v[198:201], v[86:89]
	v_mfma_f32_16x16x32_bf16 v[86:89], v[178:181], v[202:205], v[86:89]
	v_mfma_f32_16x16x32_bf16 v[70:73], v[174:177], v[206:209], v[70:73]
	v_mfma_f32_16x16x32_bf16 v[70:73], v[178:181], v[210:213], v[70:73]
	s_barrier
	s_mov_b32 m0, s91
	s_mov_b32 s75, s31
	ds_read_b128 v[182:185], v153 offset:16384
	ds_read_b128 v[186:189], v153 offset:17408
	buffer_load_dwordx4 v146, s[72:75], s13 offen lds
	s_mov_b32 m0, s93
	ds_read_b128 v[190:193], v153 offset:18432
	ds_read_b128 v[194:197], v153 offset:19456
	buffer_load_dwordx4 v148, s[72:75], s13 offen lds
	s_add_i32 s47, s13, 0x80000
	s_mov_b32 m0, s95
	ds_read_b128 v[198:201], v153 offset:20480
	ds_read_b128 v[202:205], v153 offset:21504
	buffer_load_dwordx4 v146, s[72:75], s47 offen lds
	s_mov_b32 m0, s35
	ds_read_b128 v[206:209], v153 offset:22528
	ds_read_b128 v[210:213], v153 offset:23552
	buffer_load_dwordx4 v148, s[72:75], s47 offen lds
	s_waitcnt vmcnt(6)
	s_waitcnt lgkmcnt(0)
	s_barrier
	s_waitcnt lgkmcnt(0)
	v_mfma_f32_16x16x32_bf16 v[66:69], v[138:141], v[182:185], v[66:69]
	v_mfma_f32_16x16x32_bf16 v[66:69], v[142:145], v[186:189], v[66:69]
	v_mfma_f32_16x16x32_bf16 v[50:53], v[138:141], v[190:193], v[50:53]
	v_mfma_f32_16x16x32_bf16 v[50:53], v[142:145], v[194:197], v[50:53]
	v_mfma_f32_16x16x32_bf16 v[34:37], v[138:141], v[198:201], v[34:37]
	v_mfma_f32_16x16x32_bf16 v[34:37], v[142:145], v[202:205], v[34:37]
	v_mfma_f32_16x16x32_bf16 v[18:21], v[138:141], v[206:209], v[18:21]
	v_mfma_f32_16x16x32_bf16 v[18:21], v[142:145], v[210:213], v[18:21]
	v_mfma_f32_16x16x32_bf16 v[62:65], v[158:161], v[182:185], v[62:65]
	v_mfma_f32_16x16x32_bf16 v[62:65], v[162:165], v[186:189], v[62:65]
	v_mfma_f32_16x16x32_bf16 v[46:49], v[158:161], v[190:193], v[46:49]
	v_mfma_f32_16x16x32_bf16 v[46:49], v[162:165], v[194:197], v[46:49]
	v_mfma_f32_16x16x32_bf16 v[30:33], v[158:161], v[198:201], v[30:33]
	v_mfma_f32_16x16x32_bf16 v[30:33], v[162:165], v[202:205], v[30:33]
	v_mfma_f32_16x16x32_bf16 v[14:17], v[158:161], v[206:209], v[14:17]
	v_mfma_f32_16x16x32_bf16 v[14:17], v[162:165], v[210:213], v[14:17]
	v_mfma_f32_16x16x32_bf16 v[58:61], v[166:169], v[182:185], v[58:61]
	v_mfma_f32_16x16x32_bf16 v[58:61], v[170:173], v[186:189], v[58:61]
	v_mfma_f32_16x16x32_bf16 v[42:45], v[166:169], v[190:193], v[42:45]
	v_mfma_f32_16x16x32_bf16 v[42:45], v[170:173], v[194:197], v[42:45]
	v_mfma_f32_16x16x32_bf16 v[26:29], v[166:169], v[198:201], v[26:29]
	v_mfma_f32_16x16x32_bf16 v[26:29], v[170:173], v[202:205], v[26:29]
	v_mfma_f32_16x16x32_bf16 v[10:13], v[166:169], v[206:209], v[10:13]
	v_mfma_f32_16x16x32_bf16 v[10:13], v[170:173], v[210:213], v[10:13]
	v_mfma_f32_16x16x32_bf16 v[54:57], v[174:177], v[182:185], v[54:57]
	v_mfma_f32_16x16x32_bf16 v[54:57], v[178:181], v[186:189], v[54:57]
	v_mfma_f32_16x16x32_bf16 v[38:41], v[174:177], v[190:193], v[38:41]
	v_mfma_f32_16x16x32_bf16 v[38:41], v[178:181], v[194:197], v[38:41]
	v_mfma_f32_16x16x32_bf16 v[22:25], v[174:177], v[198:201], v[22:25]
	v_mfma_f32_16x16x32_bf16 v[22:25], v[178:181], v[202:205], v[22:25]
	v_mfma_f32_16x16x32_bf16 v[4:7], v[174:177], v[206:209], v[6:9]
	v_mfma_f32_16x16x32_bf16 v[4:7], v[178:181], v[210:213], v[4:7]
	s_barrier
	ds_read_b128 v[138:141], v154
	ds_read_b128 v[142:145], v154 offset:1024
	ds_read_b128 v[158:161], v154 offset:2048
	ds_read_b128 v[162:165], v154 offset:3072
	ds_read_b128 v[166:169], v155
	ds_read_b128 v[170:173], v155 offset:1024
	ds_read_b128 v[174:177], v155 offset:2048
	ds_read_b128 v[178:181], v155 offset:3072
	s_mov_b32 m0, s77
	ds_read_b128 v[182:185], v153 offset:32768
	ds_read_b128 v[186:189], v153 offset:33792
	buffer_load_dwordx4 v1, s[28:31], s80 offen lds
	s_mov_b32 m0, s84
	ds_read_b128 v[190:193], v153 offset:34816
	ds_read_b128 v[194:197], v153 offset:35840
	buffer_load_dwordx4 v147, s[28:31], s80 offen lds
	s_add_i32 s80, s80, 0x80000
	s_mov_b32 m0, s85
	ds_read_b128 v[198:201], v153 offset:36864
	ds_read_b128 v[202:205], v153 offset:37888
	buffer_load_dwordx4 v1, s[28:31], s80 offen lds
	s_mov_b32 m0, s48
	ds_read_b128 v[206:209], v153 offset:38912
	ds_read_b128 v[210:213], v153 offset:39936
	buffer_load_dwordx4 v147, s[28:31], s80 offen lds
	s_waitcnt vmcnt(8)
	s_waitcnt lgkmcnt(0)
	s_barrier
	s_waitcnt lgkmcnt(0)
	v_mfma_f32_16x16x32_bf16 v[130:133], v[138:141], v[182:185], v[130:133]
	v_mfma_f32_16x16x32_bf16 v[130:133], v[142:145], v[186:189], v[130:133]
	v_mfma_f32_16x16x32_bf16 v[114:117], v[138:141], v[190:193], v[114:117]
	v_mfma_f32_16x16x32_bf16 v[114:117], v[142:145], v[194:197], v[114:117]
	v_mfma_f32_16x16x32_bf16 v[98:101], v[138:141], v[198:201], v[98:101]
	v_mfma_f32_16x16x32_bf16 v[98:101], v[142:145], v[202:205], v[98:101]
	v_mfma_f32_16x16x32_bf16 v[82:85], v[138:141], v[206:209], v[82:85]
	v_mfma_f32_16x16x32_bf16 v[82:85], v[142:145], v[210:213], v[82:85]
	v_mfma_f32_16x16x32_bf16 v[126:129], v[158:161], v[182:185], v[126:129]
	v_mfma_f32_16x16x32_bf16 v[126:129], v[162:165], v[186:189], v[126:129]
	v_mfma_f32_16x16x32_bf16 v[110:113], v[158:161], v[190:193], v[110:113]
	v_mfma_f32_16x16x32_bf16 v[110:113], v[162:165], v[194:197], v[110:113]
	v_mfma_f32_16x16x32_bf16 v[94:97], v[158:161], v[198:201], v[94:97]
	v_mfma_f32_16x16x32_bf16 v[94:97], v[162:165], v[202:205], v[94:97]
	v_mfma_f32_16x16x32_bf16 v[78:81], v[158:161], v[206:209], v[78:81]
	v_mfma_f32_16x16x32_bf16 v[78:81], v[162:165], v[210:213], v[78:81]
	v_mfma_f32_16x16x32_bf16 v[122:125], v[166:169], v[182:185], v[122:125]
	v_mfma_f32_16x16x32_bf16 v[122:125], v[170:173], v[186:189], v[122:125]
	v_mfma_f32_16x16x32_bf16 v[106:109], v[166:169], v[190:193], v[106:109]
	v_mfma_f32_16x16x32_bf16 v[106:109], v[170:173], v[194:197], v[106:109]
	v_mfma_f32_16x16x32_bf16 v[90:93], v[166:169], v[198:201], v[90:93]
	v_mfma_f32_16x16x32_bf16 v[90:93], v[170:173], v[202:205], v[90:93]
	v_mfma_f32_16x16x32_bf16 v[74:77], v[166:169], v[206:209], v[74:77]
	v_mfma_f32_16x16x32_bf16 v[74:77], v[170:173], v[210:213], v[74:77]
	v_mfma_f32_16x16x32_bf16 v[118:121], v[174:177], v[182:185], v[118:121]
	v_mfma_f32_16x16x32_bf16 v[118:121], v[178:181], v[186:189], v[118:121]
	v_mfma_f32_16x16x32_bf16 v[102:105], v[174:177], v[190:193], v[102:105]
	v_mfma_f32_16x16x32_bf16 v[102:105], v[178:181], v[194:197], v[102:105]
	v_mfma_f32_16x16x32_bf16 v[86:89], v[174:177], v[198:201], v[86:89]
	v_mfma_f32_16x16x32_bf16 v[86:89], v[178:181], v[202:205], v[86:89]
	v_mfma_f32_16x16x32_bf16 v[70:73], v[174:177], v[206:209], v[70:73]
	v_mfma_f32_16x16x32_bf16 v[70:73], v[178:181], v[210:213], v[70:73]
	s_barrier
	s_mov_b32 m0, s78
	s_add_i32 s47, s13, 0x80
	ds_read_b128 v[182:185], v153 offset:49152
	ds_read_b128 v[186:189], v153 offset:50176
	buffer_load_dwordx4 v146, s[72:75], s47 offen lds
	s_mov_b32 m0, s79
	ds_read_b128 v[190:193], v153 offset:51200
	ds_read_b128 v[194:197], v153 offset:52224
	buffer_load_dwordx4 v148, s[72:75], s47 offen lds
	s_add_i32 s13, s13, 0x80080
	s_mov_b32 m0, s86
	ds_read_b128 v[198:201], v153 offset:53248
	ds_read_b128 v[202:205], v153 offset:54272
	buffer_load_dwordx4 v146, s[72:75], s13 offen lds
	s_mov_b32 m0, s87
	ds_read_b128 v[206:209], v153 offset:55296
	ds_read_b128 v[210:213], v153 offset:56320
	buffer_load_dwordx4 v148, s[72:75], s13 offen lds
	s_waitcnt vmcnt(6)
	s_waitcnt lgkmcnt(0)
	s_barrier
	s_waitcnt lgkmcnt(0)
	v_mfma_f32_16x16x32_bf16 v[66:69], v[138:141], v[182:185], v[66:69]
	v_mfma_f32_16x16x32_bf16 v[66:69], v[142:145], v[186:189], v[66:69]
	v_mfma_f32_16x16x32_bf16 v[50:53], v[138:141], v[190:193], v[50:53]
	v_mfma_f32_16x16x32_bf16 v[50:53], v[142:145], v[194:197], v[50:53]
	v_mfma_f32_16x16x32_bf16 v[34:37], v[138:141], v[198:201], v[34:37]
	v_mfma_f32_16x16x32_bf16 v[34:37], v[142:145], v[202:205], v[34:37]
	v_mfma_f32_16x16x32_bf16 v[18:21], v[138:141], v[206:209], v[18:21]
	v_mfma_f32_16x16x32_bf16 v[18:21], v[142:145], v[210:213], v[18:21]
	v_mfma_f32_16x16x32_bf16 v[62:65], v[158:161], v[182:185], v[62:65]
	v_mfma_f32_16x16x32_bf16 v[62:65], v[162:165], v[186:189], v[62:65]
	v_mfma_f32_16x16x32_bf16 v[46:49], v[158:161], v[190:193], v[46:49]
	v_mfma_f32_16x16x32_bf16 v[46:49], v[162:165], v[194:197], v[46:49]
	v_mfma_f32_16x16x32_bf16 v[30:33], v[158:161], v[198:201], v[30:33]
	v_mfma_f32_16x16x32_bf16 v[30:33], v[162:165], v[202:205], v[30:33]
	v_mfma_f32_16x16x32_bf16 v[14:17], v[158:161], v[206:209], v[14:17]
	v_mfma_f32_16x16x32_bf16 v[14:17], v[162:165], v[210:213], v[14:17]
	v_mfma_f32_16x16x32_bf16 v[58:61], v[166:169], v[182:185], v[58:61]
	v_mfma_f32_16x16x32_bf16 v[58:61], v[170:173], v[186:189], v[58:61]
	v_mfma_f32_16x16x32_bf16 v[42:45], v[166:169], v[190:193], v[42:45]
	v_mfma_f32_16x16x32_bf16 v[42:45], v[170:173], v[194:197], v[42:45]
	v_mfma_f32_16x16x32_bf16 v[26:29], v[166:169], v[198:201], v[26:29]
	v_mfma_f32_16x16x32_bf16 v[26:29], v[170:173], v[202:205], v[26:29]
	v_mfma_f32_16x16x32_bf16 v[8:11], v[166:169], v[206:209], v[10:13]
	v_mfma_f32_16x16x32_bf16 v[10:13], v[170:173], v[210:213], v[8:11]
	v_mfma_f32_16x16x32_bf16 v[54:57], v[174:177], v[182:185], v[54:57]
	v_mfma_f32_16x16x32_bf16 v[54:57], v[178:181], v[186:189], v[54:57]
	v_mfma_f32_16x16x32_bf16 v[38:41], v[174:177], v[190:193], v[38:41]
	v_mfma_f32_16x16x32_bf16 v[38:41], v[178:181], v[194:197], v[38:41]
	v_mfma_f32_16x16x32_bf16 v[22:25], v[174:177], v[198:201], v[22:25]
	v_mfma_f32_16x16x32_bf16 v[22:25], v[178:181], v[202:205], v[22:25]
	v_mfma_f32_16x16x32_bf16 v[4:7], v[174:177], v[206:209], v[4:7]
	v_mfma_f32_16x16x32_bf16 v[6:9], v[178:181], v[210:213], v[4:7]
	s_barrier
	s_add_i32 s8, s8, 2
	s_addk_i32 s10, 0x100
	s_addk_i32 s11, 0x100
	s_addk_i32 s12, 0xff00
	s_cmp_gt_u32 s8, 29
	s_cbranch_scc0 .LBB0_124
	v_readlane_b32 s6, v254, 26
	v_readlane_b32 s7, v254, 27
	s_and_b64 vcc, exec, s[6:7]
	s_cbranch_vccz .LBB0_127
	s_barrier

.LBB0_528:
	v_add_u32_e32 v3, 0x10000, v171
	ds_read_b128 v[134:137], v3
	ds_read_b128 v[138:141], v3 offset:1024
	ds_read_b128 v[142:145], v3 offset:2048
	ds_read_b128 v[146:149], v3 offset:3072
	v_add_u32_e32 v3, 0x14000, v171
	ds_read_b128 v[150:153], v3
	ds_read_b128 v[154:157], v3 offset:1024
	ds_read_b128 v[174:177], v3 offset:2048
	ds_read_b128 v[178:181], v3 offset:3072
	s_add_i32 s71, s63, s94
	s_add_i32 s97, s71, 0x100
	s_add_i32 s96, s63, s95
	s_cmp_eq_u32 s63, s93
	s_cselect_b32 s96, s90, s96
	s_cselect_b32 s97, s89, s97
	s_add_i32 vcc_lo, s71, 0x80
	s_mov_b32 m0, s79
	ds_read_b128 v[182:185], v172
	ds_read_b128 v[186:189], v172 offset:1024
	buffer_load_dwordx4 v1, s[48:51], vcc_lo offen lds
	s_mov_b32 m0, s80
	ds_read_b128 v[190:193], v172 offset:2048
	ds_read_b128 v[194:197], v172 offset:3072
	buffer_load_dwordx4 v167, s[48:51], vcc_lo offen lds
	s_add_i32 s71, s71, 0xc0080
	s_mov_b32 m0, s81
	ds_read_b128 v[198:201], v172 offset:4096
	ds_read_b128 v[202:205], v172 offset:5120
	buffer_load_dwordx4 v1, s[48:51], s71 offen lds
	s_mov_b32 m0, s82
	ds_read_b128 v[206:209], v172 offset:6144
	ds_read_b128 v[210:213], v172 offset:7168
	buffer_load_dwordx4 v167, s[48:51], s71 offen lds
	s_waitcnt vmcnt(8)
	s_waitcnt lgkmcnt(0)
	s_barrier
	s_waitcnt lgkmcnt(0)
	v_mfma_f32_16x16x32_bf16 v[130:133], v[134:137], v[182:185], v[130:133]
	v_mfma_f32_16x16x32_bf16 v[130:133], v[138:141], v[186:189], v[130:133]
	v_mfma_f32_16x16x32_bf16 v[114:117], v[134:137], v[190:193], v[114:117]
	v_mfma_f32_16x16x32_bf16 v[114:117], v[138:141], v[194:197], v[114:117]
	v_mfma_f32_16x16x32_bf16 v[98:101], v[134:137], v[198:201], v[98:101]
	v_mfma_f32_16x16x32_bf16 v[98:101], v[138:141], v[202:205], v[98:101]
	v_mfma_f32_16x16x32_bf16 v[82:85], v[134:137], v[206:209], v[82:85]
	v_mfma_f32_16x16x32_bf16 v[82:85], v[138:141], v[210:213], v[82:85]
	v_mfma_f32_16x16x32_bf16 v[126:129], v[142:145], v[182:185], v[126:129]
	v_mfma_f32_16x16x32_bf16 v[126:129], v[146:149], v[186:189], v[126:129]
	v_mfma_f32_16x16x32_bf16 v[110:113], v[142:145], v[190:193], v[110:113]
	v_mfma_f32_16x16x32_bf16 v[110:113], v[146:149], v[194:197], v[110:113]
	v_mfma_f32_16x16x32_bf16 v[94:97], v[142:145], v[198:201], v[94:97]
	v_mfma_f32_16x16x32_bf16 v[94:97], v[146:149], v[202:205], v[94:97]
	v_mfma_f32_16x16x32_bf16 v[78:81], v[142:145], v[206:209], v[78:81]
	v_mfma_f32_16x16x32_bf16 v[78:81], v[146:149], v[210:213], v[78:81]
	v_mfma_f32_16x16x32_bf16 v[122:125], v[150:153], v[182:185], v[122:125]
	v_mfma_f32_16x16x32_bf16 v[122:125], v[154:157], v[186:189], v[122:125]
	v_mfma_f32_16x16x32_bf16 v[106:109], v[150:153], v[190:193], v[106:109]
	v_mfma_f32_16x16x32_bf16 v[106:109], v[154:157], v[194:197], v[106:109]
	v_mfma_f32_16x16x32_bf16 v[90:93], v[150:153], v[198:201], v[90:93]
	v_mfma_f32_16x16x32_bf16 v[90:93], v[154:157], v[202:205], v[90:93]
	v_mfma_f32_16x16x32_bf16 v[74:77], v[150:153], v[206:209], v[74:77]
	v_mfma_f32_16x16x32_bf16 v[74:77], v[154:157], v[210:213], v[74:77]
	v_mfma_f32_16x16x32_bf16 v[118:121], v[174:177], v[182:185], v[118:121]
	v_mfma_f32_16x16x32_bf16 v[118:121], v[178:181], v[186:189], v[118:121]
	v_mfma_f32_16x16x32_bf16 v[102:105], v[174:177], v[190:193], v[102:105]
	v_mfma_f32_16x16x32_bf16 v[102:105], v[178:181], v[194:197], v[102:105]
	v_mfma_f32_16x16x32_bf16 v[86:89], v[174:177], v[198:201], v[86:89]
	v_mfma_f32_16x16x32_bf16 v[86:89], v[178:181], v[202:205], v[86:89]
	v_mfma_f32_16x16x32_bf16 v[70:73], v[174:177], v[206:209], v[70:73]
	v_mfma_f32_16x16x32_bf16 v[70:73], v[178:181], v[210:213], v[70:73]
	s_barrier
	s_mov_b32 m0, s35
	s_mov_b32 s71, s51
	ds_read_b128 v[182:185], v172 offset:16384
	ds_read_b128 v[186:189], v172 offset:17408
	buffer_load_dwordx4 v166, s[68:71], s96 offen lds
	s_mov_b32 m0, s45
	ds_read_b128 v[190:193], v172 offset:18432
	ds_read_b128 v[194:197], v172 offset:19456
	buffer_load_dwordx4 v168, s[68:71], s96 offen lds
	s_add_i32 vcc_lo, s96, 0xc0000
	s_mov_b32 m0, s64
	ds_read_b128 v[198:201], v172 offset:20480
	ds_read_b128 v[202:205], v172 offset:21504
	buffer_load_dwordx4 v166, s[68:71], vcc_lo offen lds
	s_mov_b32 m0, s65
	ds_read_b128 v[206:209], v172 offset:22528
	ds_read_b128 v[210:213], v172 offset:23552
	buffer_load_dwordx4 v168, s[68:71], vcc_lo offen lds
	s_waitcnt vmcnt(6)
	s_waitcnt lgkmcnt(0)
	s_barrier
	s_waitcnt lgkmcnt(0)
	v_mfma_f32_16x16x32_bf16 v[66:69], v[134:137], v[182:185], v[66:69]
	v_mfma_f32_16x16x32_bf16 v[66:69], v[138:141], v[186:189], v[66:69]
	v_mfma_f32_16x16x32_bf16 v[50:53], v[134:137], v[190:193], v[50:53]
	v_mfma_f32_16x16x32_bf16 v[50:53], v[138:141], v[194:197], v[50:53]
	v_mfma_f32_16x16x32_bf16 v[34:37], v[134:137], v[198:201], v[34:37]
	v_mfma_f32_16x16x32_bf16 v[34:37], v[138:141], v[202:205], v[34:37]
	v_mfma_f32_16x16x32_bf16 v[18:21], v[134:137], v[206:209], v[18:21]
	v_mfma_f32_16x16x32_bf16 v[18:21], v[138:141], v[210:213], v[18:21]
	v_mfma_f32_16x16x32_bf16 v[62:65], v[142:145], v[182:185], v[62:65]
	v_mfma_f32_16x16x32_bf16 v[62:65], v[146:149], v[186:189], v[62:65]
	v_mfma_f32_16x16x32_bf16 v[46:49], v[142:145], v[190:193], v[46:49]
	v_mfma_f32_16x16x32_bf16 v[46:49], v[146:149], v[194:197], v[46:49]
	v_mfma_f32_16x16x32_bf16 v[30:33], v[142:145], v[198:201], v[30:33]
	v_mfma_f32_16x16x32_bf16 v[30:33], v[146:149], v[202:205], v[30:33]
	v_mfma_f32_16x16x32_bf16 v[14:17], v[142:145], v[206:209], v[14:17]
	v_mfma_f32_16x16x32_bf16 v[14:17], v[146:149], v[210:213], v[14:17]
	v_mfma_f32_16x16x32_bf16 v[58:61], v[150:153], v[182:185], v[58:61]
	v_mfma_f32_16x16x32_bf16 v[58:61], v[154:157], v[186:189], v[58:61]
	v_mfma_f32_16x16x32_bf16 v[42:45], v[150:153], v[190:193], v[42:45]
	v_mfma_f32_16x16x32_bf16 v[42:45], v[154:157], v[194:197], v[42:45]
	v_mfma_f32_16x16x32_bf16 v[26:29], v[150:153], v[198:201], v[26:29]
	v_mfma_f32_16x16x32_bf16 v[26:29], v[154:157], v[202:205], v[26:29]
	v_mfma_f32_16x16x32_bf16 v[10:13], v[150:153], v[206:209], v[10:13]
	v_mfma_f32_16x16x32_bf16 v[10:13], v[154:157], v[210:213], v[10:13]
	v_mfma_f32_16x16x32_bf16 v[54:57], v[174:177], v[182:185], v[54:57]
	v_mfma_f32_16x16x32_bf16 v[54:57], v[178:181], v[186:189], v[54:57]
	v_mfma_f32_16x16x32_bf16 v[38:41], v[174:177], v[190:193], v[38:41]
	v_mfma_f32_16x16x32_bf16 v[38:41], v[178:181], v[194:197], v[38:41]
	v_mfma_f32_16x16x32_bf16 v[22:25], v[174:177], v[198:201], v[22:25]
	v_mfma_f32_16x16x32_bf16 v[22:25], v[178:181], v[202:205], v[22:25]
	v_mfma_f32_16x16x32_bf16 v[4:7], v[174:177], v[206:209], v[6:9]
	v_mfma_f32_16x16x32_bf16 v[4:7], v[178:181], v[210:213], v[4:7]
	s_barrier
	v_add_u32_e32 v3, 0x18000, v171
	ds_read_b128 v[134:137], v3
	ds_read_b128 v[138:141], v3 offset:1024
	ds_read_b128 v[142:145], v3 offset:2048
	ds_read_b128 v[146:149], v3 offset:3072
	v_add_u32_e32 v3, 0x1c000, v171
	ds_read_b128 v[150:153], v3
	ds_read_b128 v[154:157], v3 offset:1024
	ds_read_b128 v[174:177], v3 offset:2048
	ds_read_b128 v[178:181], v3 offset:3072
	s_mov_b32 m0, s29
	ds_read_b128 v[182:185], v172 offset:32768
	ds_read_b128 v[186:189], v172 offset:33792
	buffer_load_dwordx4 v1, s[48:51], s97 offen lds
	s_mov_b32 m0, s66
	ds_read_b128 v[190:193], v172 offset:34816
	ds_read_b128 v[194:197], v172 offset:35840
	buffer_load_dwordx4 v167, s[48:51], s97 offen lds
	s_add_i32 s97, s97, 0xc0000
	s_mov_b32 m0, s67
	ds_read_b128 v[198:201], v172 offset:36864
	ds_read_b128 v[202:205], v172 offset:37888
	buffer_load_dwordx4 v1, s[48:51], s97 offen lds
	s_mov_b32 m0, s72
	ds_read_b128 v[206:209], v172 offset:38912
	ds_read_b128 v[210:213], v172 offset:39936
	buffer_load_dwordx4 v167, s[48:51], s97 offen lds
	s_waitcnt vmcnt(8)
	s_waitcnt lgkmcnt(0)
	s_barrier
	s_waitcnt lgkmcnt(0)
	v_mfma_f32_16x16x32_bf16 v[130:133], v[134:137], v[182:185], v[130:133]
	v_mfma_f32_16x16x32_bf16 v[130:133], v[138:141], v[186:189], v[130:133]
	v_mfma_f32_16x16x32_bf16 v[114:117], v[134:137], v[190:193], v[114:117]
	v_mfma_f32_16x16x32_bf16 v[114:117], v[138:141], v[194:197], v[114:117]
	v_mfma_f32_16x16x32_bf16 v[98:101], v[134:137], v[198:201], v[98:101]
	v_mfma_f32_16x16x32_bf16 v[98:101], v[138:141], v[202:205], v[98:101]
	v_mfma_f32_16x16x32_bf16 v[82:85], v[134:137], v[206:209], v[82:85]
	v_mfma_f32_16x16x32_bf16 v[82:85], v[138:141], v[210:213], v[82:85]
	v_mfma_f32_16x16x32_bf16 v[126:129], v[142:145], v[182:185], v[126:129]
	v_mfma_f32_16x16x32_bf16 v[126:129], v[146:149], v[186:189], v[126:129]
	v_mfma_f32_16x16x32_bf16 v[110:113], v[142:145], v[190:193], v[110:113]
	v_mfma_f32_16x16x32_bf16 v[110:113], v[146:149], v[194:197], v[110:113]
	v_mfma_f32_16x16x32_bf16 v[94:97], v[142:145], v[198:201], v[94:97]
	v_mfma_f32_16x16x32_bf16 v[94:97], v[146:149], v[202:205], v[94:97]
	v_mfma_f32_16x16x32_bf16 v[78:81], v[142:145], v[206:209], v[78:81]
	v_mfma_f32_16x16x32_bf16 v[78:81], v[146:149], v[210:213], v[78:81]
	v_mfma_f32_16x16x32_bf16 v[122:125], v[150:153], v[182:185], v[122:125]
	v_mfma_f32_16x16x32_bf16 v[122:125], v[154:157], v[186:189], v[122:125]
	v_mfma_f32_16x16x32_bf16 v[106:109], v[150:153], v[190:193], v[106:109]
	v_mfma_f32_16x16x32_bf16 v[106:109], v[154:157], v[194:197], v[106:109]
	v_mfma_f32_16x16x32_bf16 v[90:93], v[150:153], v[198:201], v[90:93]
	v_mfma_f32_16x16x32_bf16 v[90:93], v[154:157], v[202:205], v[90:93]
	v_mfma_f32_16x16x32_bf16 v[74:77], v[150:153], v[206:209], v[74:77]
	v_mfma_f32_16x16x32_bf16 v[74:77], v[154:157], v[210:213], v[74:77]
	v_mfma_f32_16x16x32_bf16 v[118:121], v[174:177], v[182:185], v[118:121]
	v_mfma_f32_16x16x32_bf16 v[118:121], v[178:181], v[186:189], v[118:121]
	v_mfma_f32_16x16x32_bf16 v[102:105], v[174:177], v[190:193], v[102:105]
	v_mfma_f32_16x16x32_bf16 v[102:105], v[178:181], v[194:197], v[102:105]
	v_mfma_f32_16x16x32_bf16 v[86:89], v[174:177], v[198:201], v[86:89]
	v_mfma_f32_16x16x32_bf16 v[86:89], v[178:181], v[202:205], v[86:89]
	v_mfma_f32_16x16x32_bf16 v[70:73], v[174:177], v[206:209], v[70:73]
	v_mfma_f32_16x16x32_bf16 v[70:73], v[178:181], v[210:213], v[70:73]
	s_barrier
	s_mov_b32 m0, s74
	s_add_i32 s97, s96, 0x80
	ds_read_b128 v[182:185], v172 offset:49152
	ds_read_b128 v[186:189], v172 offset:50176
	buffer_load_dwordx4 v166, s[68:71], s97 offen lds
	s_mov_b32 m0, s75
	ds_read_b128 v[190:193], v172 offset:51200
	ds_read_b128 v[194:197], v172 offset:52224
	buffer_load_dwordx4 v168, s[68:71], s97 offen lds
	s_add_i32 s96, s96, 0xc0080
	s_mov_b32 m0, s77
	ds_read_b128 v[198:201], v172 offset:53248
	ds_read_b128 v[202:205], v172 offset:54272
	buffer_load_dwordx4 v166, s[68:71], s96 offen lds
	s_mov_b32 m0, s78
	ds_read_b128 v[206:209], v172 offset:55296
	ds_read_b128 v[210:213], v172 offset:56320
	buffer_load_dwordx4 v168, s[68:71], s96 offen lds
	s_waitcnt vmcnt(6)
	s_waitcnt lgkmcnt(0)
	s_barrier
	s_waitcnt lgkmcnt(0)
	v_mfma_f32_16x16x32_bf16 v[66:69], v[134:137], v[182:185], v[66:69]
	v_mfma_f32_16x16x32_bf16 v[66:69], v[138:141], v[186:189], v[66:69]
	v_mfma_f32_16x16x32_bf16 v[50:53], v[134:137], v[190:193], v[50:53]
	v_mfma_f32_16x16x32_bf16 v[50:53], v[138:141], v[194:197], v[50:53]
	v_mfma_f32_16x16x32_bf16 v[34:37], v[134:137], v[198:201], v[34:37]
	v_mfma_f32_16x16x32_bf16 v[34:37], v[138:141], v[202:205], v[34:37]
	v_mfma_f32_16x16x32_bf16 v[18:21], v[134:137], v[206:209], v[18:21]
	v_mfma_f32_16x16x32_bf16 v[18:21], v[138:141], v[210:213], v[18:21]
	v_mfma_f32_16x16x32_bf16 v[62:65], v[142:145], v[182:185], v[62:65]
	v_mfma_f32_16x16x32_bf16 v[62:65], v[146:149], v[186:189], v[62:65]
	v_mfma_f32_16x16x32_bf16 v[46:49], v[142:145], v[190:193], v[46:49]
	v_mfma_f32_16x16x32_bf16 v[46:49], v[146:149], v[194:197], v[46:49]
	v_mfma_f32_16x16x32_bf16 v[30:33], v[142:145], v[198:201], v[30:33]
	v_mfma_f32_16x16x32_bf16 v[30:33], v[146:149], v[202:205], v[30:33]
	v_mfma_f32_16x16x32_bf16 v[14:17], v[142:145], v[206:209], v[14:17]
	v_mfma_f32_16x16x32_bf16 v[14:17], v[146:149], v[210:213], v[14:17]
	v_mfma_f32_16x16x32_bf16 v[58:61], v[150:153], v[182:185], v[58:61]
	v_mfma_f32_16x16x32_bf16 v[58:61], v[154:157], v[186:189], v[58:61]
	v_mfma_f32_16x16x32_bf16 v[42:45], v[150:153], v[190:193], v[42:45]
	v_mfma_f32_16x16x32_bf16 v[42:45], v[154:157], v[194:197], v[42:45]
	v_mfma_f32_16x16x32_bf16 v[26:29], v[150:153], v[198:201], v[26:29]
	v_mfma_f32_16x16x32_bf16 v[26:29], v[154:157], v[202:205], v[26:29]
	v_mfma_f32_16x16x32_bf16 v[8:11], v[150:153], v[206:209], v[10:13]
	v_mfma_f32_16x16x32_bf16 v[10:13], v[154:157], v[210:213], v[8:11]
	v_mfma_f32_16x16x32_bf16 v[54:57], v[174:177], v[182:185], v[54:57]
	v_mfma_f32_16x16x32_bf16 v[54:57], v[178:181], v[186:189], v[54:57]
	v_mfma_f32_16x16x32_bf16 v[38:41], v[174:177], v[190:193], v[38:41]
	v_mfma_f32_16x16x32_bf16 v[38:41], v[178:181], v[194:197], v[38:41]
	v_mfma_f32_16x16x32_bf16 v[22:25], v[174:177], v[198:201], v[22:25]
	v_mfma_f32_16x16x32_bf16 v[22:25], v[178:181], v[202:205], v[22:25]
	v_mfma_f32_16x16x32_bf16 v[4:7], v[174:177], v[206:209], v[4:7]
	v_mfma_f32_16x16x32_bf16 v[6:9], v[178:181], v[210:213], v[4:7]
	s_barrier
	s_add_i32 s92, s92, 2
	s_addk_i32 s95, 0x100
	s_addk_i32 s94, 0x100
	s_addk_i32 s93, 0xff00
	s_cmp_ge_u32 s92, s62
	s_cbranch_scc0 .LBB0_528
	s_branch .LBB0_523

.LBB0_605:
	v_add_u32_e32 v141, 0x10000, v139
	ds_read_b128 v[142:145], v141
	ds_read_b128 v[146:149], v141 offset:1024
	ds_read_b128 v[154:157], v141 offset:2048
	ds_read_b128 v[158:161], v141 offset:3072
	v_add_u32_e32 v141, 0x14000, v139
	ds_read_b128 v[162:165], v141
	ds_read_b128 v[166:169], v141 offset:1024
	ds_read_b128 v[170:173], v141 offset:2048
	ds_read_b128 v[174:177], v141 offset:3072
	s_add_i32 s47, s64, s82
	s_add_i32 s84, s47, 0x100
	s_add_i32 s83, s11, s82
	s_cmpk_eq_i32 s82, 0xf00
	s_cselect_b32 s83, s80, s83
	s_cselect_b32 s84, s79, s84
	s_add_i32 s85, s47, 0x80
	s_mov_b32 m0, s71
	ds_read_b128 v[178:181], v140
	ds_read_b128 v[182:185], v140 offset:1024
	buffer_load_dwordx4 v135, s[12:15], s85 offen lds
	s_mov_b32 m0, s72
	ds_read_b128 v[186:189], v140 offset:2048
	ds_read_b128 v[190:193], v140 offset:3072
	buffer_load_dwordx4 v137, s[12:15], s85 offen lds
	s_add_i32 s47, s47, 0x80080
	s_mov_b32 m0, s73
	ds_read_b128 v[194:197], v140 offset:4096
	ds_read_b128 v[198:201], v140 offset:5120
	buffer_load_dwordx4 v135, s[12:15], s47 offen lds
	s_mov_b32 m0, s74
	ds_read_b128 v[202:205], v140 offset:6144
	ds_read_b128 v[206:209], v140 offset:7168
	buffer_load_dwordx4 v137, s[12:15], s47 offen lds
	s_waitcnt vmcnt(8)
	s_waitcnt lgkmcnt(0)
	s_barrier
	s_waitcnt lgkmcnt(0)
	v_mfma_f32_16x16x32_bf16 v[126:129], v[142:145], v[178:181], v[126:129]
	v_mfma_f32_16x16x32_bf16 v[126:129], v[146:149], v[182:185], v[126:129]
	v_mfma_f32_16x16x32_bf16 v[110:113], v[142:145], v[186:189], v[110:113]
	v_mfma_f32_16x16x32_bf16 v[110:113], v[146:149], v[190:193], v[110:113]
	v_mfma_f32_16x16x32_bf16 v[94:97], v[142:145], v[194:197], v[94:97]
	v_mfma_f32_16x16x32_bf16 v[94:97], v[146:149], v[198:201], v[94:97]
	v_mfma_f32_16x16x32_bf16 v[78:81], v[142:145], v[202:205], v[78:81]
	v_mfma_f32_16x16x32_bf16 v[78:81], v[146:149], v[206:209], v[78:81]
	v_mfma_f32_16x16x32_bf16 v[122:125], v[154:157], v[178:181], v[122:125]
	v_mfma_f32_16x16x32_bf16 v[122:125], v[158:161], v[182:185], v[122:125]
	v_mfma_f32_16x16x32_bf16 v[106:109], v[154:157], v[186:189], v[106:109]
	v_mfma_f32_16x16x32_bf16 v[106:109], v[158:161], v[190:193], v[106:109]
	v_mfma_f32_16x16x32_bf16 v[90:93], v[154:157], v[194:197], v[90:93]
	v_mfma_f32_16x16x32_bf16 v[90:93], v[158:161], v[198:201], v[90:93]
	v_mfma_f32_16x16x32_bf16 v[74:77], v[154:157], v[202:205], v[74:77]
	v_mfma_f32_16x16x32_bf16 v[74:77], v[158:161], v[206:209], v[74:77]
	v_mfma_f32_16x16x32_bf16 v[118:121], v[162:165], v[178:181], v[118:121]
	v_mfma_f32_16x16x32_bf16 v[118:121], v[166:169], v[182:185], v[118:121]
	v_mfma_f32_16x16x32_bf16 v[102:105], v[162:165], v[186:189], v[102:105]
	v_mfma_f32_16x16x32_bf16 v[102:105], v[166:169], v[190:193], v[102:105]
	v_mfma_f32_16x16x32_bf16 v[86:89], v[162:165], v[194:197], v[86:89]
	v_mfma_f32_16x16x32_bf16 v[86:89], v[166:169], v[198:201], v[86:89]
	v_mfma_f32_16x16x32_bf16 v[70:73], v[162:165], v[202:205], v[70:73]
	v_mfma_f32_16x16x32_bf16 v[70:73], v[166:169], v[206:209], v[70:73]
	v_mfma_f32_16x16x32_bf16 v[114:117], v[170:173], v[178:181], v[114:117]
	v_mfma_f32_16x16x32_bf16 v[114:117], v[174:177], v[182:185], v[114:117]
	v_mfma_f32_16x16x32_bf16 v[98:101], v[170:173], v[186:189], v[98:101]
	v_mfma_f32_16x16x32_bf16 v[98:101], v[174:177], v[190:193], v[98:101]
	v_mfma_f32_16x16x32_bf16 v[82:85], v[170:173], v[194:197], v[82:85]
	v_mfma_f32_16x16x32_bf16 v[82:85], v[174:177], v[198:201], v[82:85]
	v_mfma_f32_16x16x32_bf16 v[66:69], v[170:173], v[202:205], v[66:69]
	v_mfma_f32_16x16x32_bf16 v[66:69], v[174:177], v[206:209], v[66:69]
	s_barrier
	s_mov_b32 m0, s58
	s_mov_b32 s47, s15
	ds_read_b128 v[178:181], v140 offset:16384
	ds_read_b128 v[182:185], v140 offset:17408
	buffer_load_dwordx4 v136, s[44:47], s83 offen lds
	s_mov_b32 m0, s60
	ds_read_b128 v[186:189], v140 offset:18432
	ds_read_b128 v[190:193], v140 offset:19456
	buffer_load_dwordx4 v138, s[44:47], s83 offen lds
	s_add_i32 s85, s83, 0x80000
	s_mov_b32 m0, s61
	ds_read_b128 v[194:197], v140 offset:20480
	ds_read_b128 v[198:201], v140 offset:21504
	buffer_load_dwordx4 v136, s[44:47], s85 offen lds
	s_mov_b32 m0, s62
	ds_read_b128 v[202:205], v140 offset:22528
	ds_read_b128 v[206:209], v140 offset:23552
	buffer_load_dwordx4 v138, s[44:47], s85 offen lds
	s_waitcnt vmcnt(6)
	s_waitcnt lgkmcnt(0)
	s_barrier
	s_waitcnt lgkmcnt(0)
	v_mfma_f32_16x16x32_bf16 v[62:65], v[142:145], v[178:181], v[62:65]
	v_mfma_f32_16x16x32_bf16 v[62:65], v[146:149], v[182:185], v[62:65]
	v_mfma_f32_16x16x32_bf16 v[46:49], v[142:145], v[186:189], v[46:49]
	v_mfma_f32_16x16x32_bf16 v[46:49], v[146:149], v[190:193], v[46:49]
	v_mfma_f32_16x16x32_bf16 v[30:33], v[142:145], v[194:197], v[30:33]
	v_mfma_f32_16x16x32_bf16 v[30:33], v[146:149], v[198:201], v[30:33]
	v_mfma_f32_16x16x32_bf16 v[14:17], v[142:145], v[202:205], v[14:17]
	v_mfma_f32_16x16x32_bf16 v[14:17], v[146:149], v[206:209], v[14:17]
	v_mfma_f32_16x16x32_bf16 v[58:61], v[154:157], v[178:181], v[58:61]
	v_mfma_f32_16x16x32_bf16 v[58:61], v[158:161], v[182:185], v[58:61]
	v_mfma_f32_16x16x32_bf16 v[42:45], v[154:157], v[186:189], v[42:45]
	v_mfma_f32_16x16x32_bf16 v[42:45], v[158:161], v[190:193], v[42:45]
	v_mfma_f32_16x16x32_bf16 v[26:29], v[154:157], v[194:197], v[26:29]
	v_mfma_f32_16x16x32_bf16 v[26:29], v[158:161], v[198:201], v[26:29]
	v_mfma_f32_16x16x32_bf16 v[10:13], v[154:157], v[202:205], v[10:13]
	v_mfma_f32_16x16x32_bf16 v[10:13], v[158:161], v[206:209], v[10:13]
	v_mfma_f32_16x16x32_bf16 v[54:57], v[162:165], v[178:181], v[54:57]
	v_mfma_f32_16x16x32_bf16 v[54:57], v[166:169], v[182:185], v[54:57]
	v_mfma_f32_16x16x32_bf16 v[38:41], v[162:165], v[186:189], v[38:41]
	v_mfma_f32_16x16x32_bf16 v[38:41], v[166:169], v[190:193], v[38:41]
	v_mfma_f32_16x16x32_bf16 v[22:25], v[162:165], v[194:197], v[22:25]
	v_mfma_f32_16x16x32_bf16 v[22:25], v[166:169], v[198:201], v[22:25]
	v_mfma_f32_16x16x32_bf16 v[6:9], v[162:165], v[202:205], v[6:9]
	v_mfma_f32_16x16x32_bf16 v[6:9], v[166:169], v[206:209], v[6:9]
	v_mfma_f32_16x16x32_bf16 v[50:53], v[170:173], v[178:181], v[50:53]
	v_mfma_f32_16x16x32_bf16 v[50:53], v[174:177], v[182:185], v[50:53]
	v_mfma_f32_16x16x32_bf16 v[34:37], v[170:173], v[186:189], v[34:37]
	v_mfma_f32_16x16x32_bf16 v[34:37], v[174:177], v[190:193], v[34:37]
	v_mfma_f32_16x16x32_bf16 v[18:21], v[170:173], v[194:197], v[18:21]
	v_mfma_f32_16x16x32_bf16 v[18:21], v[174:177], v[198:201], v[18:21]
	v_mfma_f32_16x16x32_bf16 v[2:5], v[170:173], v[202:205], v[2:5]
	v_mfma_f32_16x16x32_bf16 v[2:5], v[174:177], v[206:209], v[2:5]
	s_barrier
	v_add_u32_e32 v141, 0x18000, v139
	ds_read_b128 v[142:145], v141
	ds_read_b128 v[146:149], v141 offset:1024
	ds_read_b128 v[154:157], v141 offset:2048
	ds_read_b128 v[158:161], v141 offset:3072
	v_add_u32_e32 v141, 0x1c000, v139
	ds_read_b128 v[162:165], v141
	ds_read_b128 v[166:169], v141 offset:1024
	ds_read_b128 v[170:173], v141 offset:2048
	ds_read_b128 v[174:177], v141 offset:3072
	s_mov_b32 m0, s51
	ds_read_b128 v[178:181], v140 offset:32768
	ds_read_b128 v[182:185], v140 offset:33792
	buffer_load_dwordx4 v135, s[12:15], s84 offen lds
	s_mov_b32 m0, s63
	ds_read_b128 v[186:189], v140 offset:34816
	ds_read_b128 v[190:193], v140 offset:35840
	buffer_load_dwordx4 v137, s[12:15], s84 offen lds
	s_add_i32 s84, s84, 0x80000
	s_mov_b32 m0, s65
	ds_read_b128 v[194:197], v140 offset:36864
	ds_read_b128 v[198:201], v140 offset:37888
	buffer_load_dwordx4 v135, s[12:15], s84 offen lds
	s_mov_b32 m0, s66
	ds_read_b128 v[202:205], v140 offset:38912
	ds_read_b128 v[206:209], v140 offset:39936
	buffer_load_dwordx4 v137, s[12:15], s84 offen lds
	s_waitcnt vmcnt(8)
	s_waitcnt lgkmcnt(0)
	s_barrier
	s_waitcnt lgkmcnt(0)
	v_mfma_f32_16x16x32_bf16 v[126:129], v[142:145], v[178:181], v[126:129]
	v_mfma_f32_16x16x32_bf16 v[126:129], v[146:149], v[182:185], v[126:129]
	v_mfma_f32_16x16x32_bf16 v[110:113], v[142:145], v[186:189], v[110:113]
	v_mfma_f32_16x16x32_bf16 v[110:113], v[146:149], v[190:193], v[110:113]
	v_mfma_f32_16x16x32_bf16 v[94:97], v[142:145], v[194:197], v[94:97]
	v_mfma_f32_16x16x32_bf16 v[94:97], v[146:149], v[198:201], v[94:97]
	v_mfma_f32_16x16x32_bf16 v[78:81], v[142:145], v[202:205], v[78:81]
	v_mfma_f32_16x16x32_bf16 v[78:81], v[146:149], v[206:209], v[78:81]
	v_mfma_f32_16x16x32_bf16 v[122:125], v[154:157], v[178:181], v[122:125]
	v_mfma_f32_16x16x32_bf16 v[122:125], v[158:161], v[182:185], v[122:125]
	v_mfma_f32_16x16x32_bf16 v[106:109], v[154:157], v[186:189], v[106:109]
	v_mfma_f32_16x16x32_bf16 v[106:109], v[158:161], v[190:193], v[106:109]
	v_mfma_f32_16x16x32_bf16 v[90:93], v[154:157], v[194:197], v[90:93]
	v_mfma_f32_16x16x32_bf16 v[90:93], v[158:161], v[198:201], v[90:93]
	v_mfma_f32_16x16x32_bf16 v[74:77], v[154:157], v[202:205], v[74:77]
	v_mfma_f32_16x16x32_bf16 v[74:77], v[158:161], v[206:209], v[74:77]
	v_mfma_f32_16x16x32_bf16 v[118:121], v[162:165], v[178:181], v[118:121]
	v_mfma_f32_16x16x32_bf16 v[118:121], v[166:169], v[182:185], v[118:121]
	v_mfma_f32_16x16x32_bf16 v[102:105], v[162:165], v[186:189], v[102:105]
	v_mfma_f32_16x16x32_bf16 v[102:105], v[166:169], v[190:193], v[102:105]
	v_mfma_f32_16x16x32_bf16 v[86:89], v[162:165], v[194:197], v[86:89]
	v_mfma_f32_16x16x32_bf16 v[86:89], v[166:169], v[198:201], v[86:89]
	v_mfma_f32_16x16x32_bf16 v[70:73], v[162:165], v[202:205], v[70:73]
	v_mfma_f32_16x16x32_bf16 v[70:73], v[166:169], v[206:209], v[70:73]
	v_mfma_f32_16x16x32_bf16 v[114:117], v[170:173], v[178:181], v[114:117]
	v_mfma_f32_16x16x32_bf16 v[114:117], v[174:177], v[182:185], v[114:117]
	v_mfma_f32_16x16x32_bf16 v[98:101], v[170:173], v[186:189], v[98:101]
	v_mfma_f32_16x16x32_bf16 v[98:101], v[174:177], v[190:193], v[98:101]
	v_mfma_f32_16x16x32_bf16 v[82:85], v[170:173], v[194:197], v[82:85]
	v_mfma_f32_16x16x32_bf16 v[82:85], v[174:177], v[198:201], v[82:85]
	v_mfma_f32_16x16x32_bf16 v[66:69], v[170:173], v[202:205], v[66:69]
	v_mfma_f32_16x16x32_bf16 v[66:69], v[174:177], v[206:209], v[66:69]
	s_barrier
	s_mov_b32 m0, s67
	s_or_b32 s84, s83, 0x80
	ds_read_b128 v[178:181], v140 offset:49152
	ds_read_b128 v[182:185], v140 offset:50176
	buffer_load_dwordx4 v136, s[44:47], s84 offen lds
	s_mov_b32 m0, s68
	ds_read_b128 v[186:189], v140 offset:51200
	ds_read_b128 v[190:193], v140 offset:52224
	buffer_load_dwordx4 v138, s[44:47], s84 offen lds
	s_add_i32 s83, s83, 0x80080
	s_mov_b32 m0, s69
	ds_read_b128 v[194:197], v140 offset:53248
	ds_read_b128 v[198:201], v140 offset:54272
	buffer_load_dwordx4 v136, s[44:47], s83 offen lds
	s_mov_b32 m0, s70
	ds_read_b128 v[202:205], v140 offset:55296
	ds_read_b128 v[206:209], v140 offset:56320
	buffer_load_dwordx4 v138, s[44:47], s83 offen lds
	s_waitcnt vmcnt(6)
	s_waitcnt lgkmcnt(0)
	s_barrier
	s_waitcnt lgkmcnt(0)
	v_mfma_f32_16x16x32_bf16 v[62:65], v[142:145], v[178:181], v[62:65]
	v_mfma_f32_16x16x32_bf16 v[62:65], v[146:149], v[182:185], v[62:65]
	v_mfma_f32_16x16x32_bf16 v[46:49], v[142:145], v[186:189], v[46:49]
	v_mfma_f32_16x16x32_bf16 v[46:49], v[146:149], v[190:193], v[46:49]
	v_mfma_f32_16x16x32_bf16 v[30:33], v[142:145], v[194:197], v[30:33]
	v_mfma_f32_16x16x32_bf16 v[30:33], v[146:149], v[198:201], v[30:33]
	v_mfma_f32_16x16x32_bf16 v[14:17], v[142:145], v[202:205], v[14:17]
	v_mfma_f32_16x16x32_bf16 v[14:17], v[146:149], v[206:209], v[14:17]
	v_mfma_f32_16x16x32_bf16 v[58:61], v[154:157], v[178:181], v[58:61]
	v_mfma_f32_16x16x32_bf16 v[58:61], v[158:161], v[182:185], v[58:61]
	v_mfma_f32_16x16x32_bf16 v[42:45], v[154:157], v[186:189], v[42:45]
	v_mfma_f32_16x16x32_bf16 v[42:45], v[158:161], v[190:193], v[42:45]
	v_mfma_f32_16x16x32_bf16 v[26:29], v[154:157], v[194:197], v[26:29]
	v_mfma_f32_16x16x32_bf16 v[26:29], v[158:161], v[198:201], v[26:29]
	v_mfma_f32_16x16x32_bf16 v[10:13], v[154:157], v[202:205], v[10:13]
	v_mfma_f32_16x16x32_bf16 v[10:13], v[158:161], v[206:209], v[10:13]
	v_mfma_f32_16x16x32_bf16 v[54:57], v[162:165], v[178:181], v[54:57]
	v_mfma_f32_16x16x32_bf16 v[54:57], v[166:169], v[182:185], v[54:57]
	v_mfma_f32_16x16x32_bf16 v[38:41], v[162:165], v[186:189], v[38:41]
	v_mfma_f32_16x16x32_bf16 v[38:41], v[166:169], v[190:193], v[38:41]
	v_mfma_f32_16x16x32_bf16 v[22:25], v[162:165], v[194:197], v[22:25]
	v_mfma_f32_16x16x32_bf16 v[22:25], v[166:169], v[198:201], v[22:25]
	v_mfma_f32_16x16x32_bf16 v[6:9], v[162:165], v[202:205], v[6:9]
	v_mfma_f32_16x16x32_bf16 v[6:9], v[166:169], v[206:209], v[6:9]
	v_mfma_f32_16x16x32_bf16 v[50:53], v[170:173], v[178:181], v[50:53]
	v_mfma_f32_16x16x32_bf16 v[50:53], v[174:177], v[182:185], v[50:53]
	v_mfma_f32_16x16x32_bf16 v[34:37], v[170:173], v[186:189], v[34:37]
	v_mfma_f32_16x16x32_bf16 v[34:37], v[174:177], v[190:193], v[34:37]
	v_mfma_f32_16x16x32_bf16 v[18:21], v[170:173], v[194:197], v[18:21]
	v_mfma_f32_16x16x32_bf16 v[18:21], v[174:177], v[198:201], v[18:21]
	v_mfma_f32_16x16x32_bf16 v[2:5], v[170:173], v[202:205], v[2:5]
	v_mfma_f32_16x16x32_bf16 v[2:5], v[174:177], v[206:209], v[2:5]
	s_barrier
	s_add_i32 s81, s81, 2
	s_addk_i32 s82, 0x100
	s_cmp_gt_u32 s81, 29
	s_cbranch_scc0 .LBB0_605
	s_andn2_b64 vcc, exec, s[4:5]
	s_cbranch_vccnz .LBB0_597
	v_mov_b32_e32 v2, 0
	s_mov_b32 s42, s77
	s_mov_b32 s3, s78
	s_mov_b32 s59, s10
	s_mov_b32 s64, s9
	s_mov_b32 s75, s8
	v_mov_b32_e32 v3, v2
	v_mov_b32_e32 v4, v2
	v_mov_b32_e32 v5, v2
	v_mov_b32_e32 v6, v2
	v_mov_b32_e32 v7, v2
	v_mov_b32_e32 v8, v2
	v_mov_b32_e32 v9, v2
	v_mov_b32_e32 v18, v2
	v_mov_b32_e32 v19, v2
	v_mov_b32_e32 v20, v2
	v_mov_b32_e32 v21, v2
	v_mov_b32_e32 v22, v2
	v_mov_b32_e32 v23, v2
	v_mov_b32_e32 v24, v2
	v_mov_b32_e32 v25, v2
	v_mov_b32_e32 v34, v2
	v_mov_b32_e32 v35, v2
	v_mov_b32_e32 v36, v2
	v_mov_b32_e32 v37, v2
	v_mov_b32_e32 v38, v2
	v_mov_b32_e32 v39, v2
	v_mov_b32_e32 v40, v2
	v_mov_b32_e32 v41, v2
	v_mov_b32_e32 v50, v2
	v_mov_b32_e32 v51, v2
	v_mov_b32_e32 v52, v2
	v_mov_b32_e32 v53, v2
	v_mov_b32_e32 v54, v2
	v_mov_b32_e32 v55, v2
	v_mov_b32_e32 v56, v2
	v_mov_b32_e32 v57, v2
	v_mov_b32_e32 v10, v2
	v_mov_b32_e32 v11, v2
	v_mov_b32_e32 v12, v2
	v_mov_b32_e32 v13, v2
	v_mov_b32_e32 v14, v2
	v_mov_b32_e32 v15, v2
	v_mov_b32_e32 v16, v2
	v_mov_b32_e32 v17, v2
	v_mov_b32_e32 v26, v2
	v_mov_b32_e32 v27, v2
	v_mov_b32_e32 v28, v2
	v_mov_b32_e32 v29, v2
	v_mov_b32_e32 v30, v2
	v_mov_b32_e32 v31, v2
	v_mov_b32_e32 v32, v2
	v_mov_b32_e32 v33, v2
	v_mov_b32_e32 v42, v2
	v_mov_b32_e32 v43, v2
	v_mov_b32_e32 v44, v2
	v_mov_b32_e32 v45, v2
	v_mov_b32_e32 v46, v2
	v_mov_b32_e32 v47, v2
	v_mov_b32_e32 v48, v2
	v_mov_b32_e32 v49, v2
	v_mov_b32_e32 v58, v2
	v_mov_b32_e32 v59, v2
	v_mov_b32_e32 v60, v2
	v_mov_b32_e32 v61, v2
	v_mov_b32_e32 v62, v2
	v_mov_b32_e32 v63, v2
	v_mov_b32_e32 v64, v2
	v_mov_b32_e32 v65, v2
	v_mov_b32_e32 v66, v2
	v_mov_b32_e32 v67, v2
	v_mov_b32_e32 v68, v2
	v_mov_b32_e32 v69, v2
	v_mov_b32_e32 v70, v2
	v_mov_b32_e32 v71, v2
	v_mov_b32_e32 v72, v2
	v_mov_b32_e32 v73, v2
	v_mov_b32_e32 v82, v2
	v_mov_b32_e32 v83, v2
	v_mov_b32_e32 v84, v2
	v_mov_b32_e32 v85, v2
	v_mov_b32_e32 v86, v2
	v_mov_b32_e32 v87, v2
	v_mov_b32_e32 v88, v2
	v_mov_b32_e32 v89, v2
	v_mov_b32_e32 v98, v2
	v_mov_b32_e32 v99, v2
	v_mov_b32_e32 v100, v2
	v_mov_b32_e32 v101, v2
	v_mov_b32_e32 v102, v2
	v_mov_b32_e32 v103, v2
	v_mov_b32_e32 v104, v2
	v_mov_b32_e32 v105, v2
	v_mov_b32_e32 v114, v2
	v_mov_b32_e32 v115, v2
	v_mov_b32_e32 v116, v2
	v_mov_b32_e32 v117, v2
	v_mov_b32_e32 v118, v2
	v_mov_b32_e32 v119, v2
	v_mov_b32_e32 v120, v2
	v_mov_b32_e32 v121, v2
	v_mov_b32_e32 v74, v2
	v_mov_b32_e32 v75, v2
	v_mov_b32_e32 v76, v2
	v_mov_b32_e32 v77, v2
	v_mov_b32_e32 v78, v2
	v_mov_b32_e32 v79, v2
	v_mov_b32_e32 v80, v2
	v_mov_b32_e32 v81, v2
	v_mov_b32_e32 v90, v2
	v_mov_b32_e32 v91, v2
	v_mov_b32_e32 v92, v2
	v_mov_b32_e32 v93, v2
	v_mov_b32_e32 v94, v2
	v_mov_b32_e32 v95, v2
	v_mov_b32_e32 v96, v2
	v_mov_b32_e32 v97, v2
	v_mov_b32_e32 v106, v2
	v_mov_b32_e32 v107, v2
	v_mov_b32_e32 v108, v2
	v_mov_b32_e32 v109, v2
	v_mov_b32_e32 v110, v2
	v_mov_b32_e32 v111, v2
	v_mov_b32_e32 v112, v2
	v_mov_b32_e32 v113, v2
	v_mov_b32_e32 v122, v2
	v_mov_b32_e32 v123, v2
	v_mov_b32_e32 v124, v2
	v_mov_b32_e32 v125, v2
	v_mov_b32_e32 v126, v2
	v_mov_b32_e32 v127, v2
	v_mov_b32_e32 v128, v2
	v_mov_b32_e32 v129, v2
	s_branch .LBB0_597

.LBB0_822:
	ds_read_b128 v[66:69], v242
	ds_read_b128 v[70:73], v242 offset:1024
	ds_read_b128 v[74:77], v242 offset:2048
	ds_read_b128 v[78:81], v242 offset:3072
	ds_read_b128 v[82:85], v243
	ds_read_b128 v[86:89], v243 offset:1024
	ds_read_b128 v[90:93], v243 offset:2048
	ds_read_b128 v[94:97], v243 offset:3072
	s_add_i32 s43, s68, 0xfff80080
	s_cmp_eq_u32 s69, 28
	s_cselect_b32 s91, s11, s67
	s_cselect_b32 s92, s10, s43
	s_add_i32 s43, s68, 0xfff80000
	s_mov_b32 m0, s79
	ds_read_b128 v[98:101], v244
	ds_read_b128 v[102:105], v244 offset:1024
	buffer_load_dwordx4 v1, s[48:51], s43 offen lds
	s_mov_b32 m0, s80
	ds_read_b128 v[106:109], v244 offset:2048
	ds_read_b128 v[110:113], v244 offset:3072
	buffer_load_dwordx4 v236, s[48:51], s43 offen lds
	s_mov_b32 m0, s81
	ds_read_b128 v[114:117], v244 offset:4096
	ds_read_b128 v[118:121], v244 offset:5120
	buffer_load_dwordx4 v1, s[48:51], s68 offen lds
	s_mov_b32 m0, s82
	ds_read_b128 v[122:125], v244 offset:6144
	ds_read_b128 v[126:129], v244 offset:7168
	buffer_load_dwordx4 v236, s[48:51], s68 offen lds
	s_waitcnt vmcnt(8)
	s_waitcnt lgkmcnt(0)
	s_barrier
	s_waitcnt lgkmcnt(0)
	v_mfma_f32_16x16x32_bf16 v[190:193], v[66:69], v[98:101], v[190:193]
	v_mfma_f32_16x16x32_bf16 v[190:193], v[70:73], v[102:105], v[190:193]
	v_mfma_f32_16x16x32_bf16 v[174:177], v[66:69], v[106:109], v[174:177]
	v_mfma_f32_16x16x32_bf16 v[174:177], v[70:73], v[110:113], v[174:177]
	v_mfma_f32_16x16x32_bf16 v[170:173], v[66:69], v[114:117], v[170:173]
	v_mfma_f32_16x16x32_bf16 v[170:173], v[70:73], v[118:121], v[170:173]
	v_mfma_f32_16x16x32_bf16 v[158:161], v[66:69], v[122:125], v[158:161]
	v_mfma_f32_16x16x32_bf16 v[158:161], v[70:73], v[126:129], v[158:161]
	v_mfma_f32_16x16x32_bf16 v[186:189], v[74:77], v[98:101], v[186:189]
	v_mfma_f32_16x16x32_bf16 v[186:189], v[78:81], v[102:105], v[186:189]
	v_mfma_f32_16x16x32_bf16 v[166:169], v[74:77], v[106:109], v[166:169]
	v_mfma_f32_16x16x32_bf16 v[166:169], v[78:81], v[110:113], v[166:169]
	v_mfma_f32_16x16x32_bf16 v[162:165], v[74:77], v[114:117], v[162:165]
	v_mfma_f32_16x16x32_bf16 v[162:165], v[78:81], v[118:121], v[162:165]
	v_mfma_f32_16x16x32_bf16 v[154:157], v[74:77], v[122:125], v[154:157]
	v_mfma_f32_16x16x32_bf16 v[154:157], v[78:81], v[126:129], v[154:157]
	v_mfma_f32_16x16x32_bf16 v[182:185], v[82:85], v[98:101], v[182:185]
	v_mfma_f32_16x16x32_bf16 v[182:185], v[86:89], v[102:105], v[182:185]
	v_mfma_f32_16x16x32_bf16 v[98:101], v[90:93], v[98:101], v[178:181]
	v_mfma_f32_16x16x32_bf16 v[98:101], v[94:97], v[102:105], v[98:101]
	v_mfma_f32_16x16x32_bf16 v[102:105], v[82:85], v[106:109], v[150:153]
	v_mfma_f32_16x16x32_bf16 v[102:105], v[86:89], v[110:113], v[102:105]
	v_mfma_f32_16x16x32_bf16 v[106:109], v[90:93], v[106:109], v[142:145]
	v_mfma_f32_16x16x32_bf16 v[106:109], v[94:97], v[110:113], v[106:109]
	v_mfma_f32_16x16x32_bf16 v[110:113], v[82:85], v[114:117], v[146:149]
	v_mfma_f32_16x16x32_bf16 v[110:113], v[86:89], v[118:121], v[110:113]
	v_mfma_f32_16x16x32_bf16 v[114:117], v[90:93], v[114:117], v[138:141]
	v_mfma_f32_16x16x32_bf16 v[114:117], v[94:97], v[118:121], v[114:117]
	v_mfma_f32_16x16x32_bf16 v[118:121], v[82:85], v[122:125], v[134:137]
	v_mfma_f32_16x16x32_bf16 v[118:121], v[86:89], v[126:129], v[118:121]
	v_mfma_f32_16x16x32_bf16 v[122:125], v[90:93], v[122:125], v[130:133]
	v_mfma_f32_16x16x32_bf16 v[122:125], v[94:97], v[126:129], v[122:125]
	s_barrier
	s_mov_b32 m0, s29
	s_mov_b32 s43, s51
	ds_read_b128 v[126:129], v244 offset:16384
	ds_read_b128 v[130:133], v244 offset:17408
	buffer_load_dwordx4 v227, s[40:43], s91 offen lds
	s_mov_b32 m0, s35
	ds_read_b128 v[134:137], v244 offset:18432
	ds_read_b128 v[138:141], v244 offset:19456
	buffer_load_dwordx4 v237, s[40:43], s91 offen lds
	s_add_i32 s93, s91, 0x1600000
	s_mov_b32 m0, s63
	ds_read_b128 v[142:145], v244 offset:20480
	ds_read_b128 v[146:149], v244 offset:21504
	buffer_load_dwordx4 v227, s[40:43], s93 offen lds
	s_mov_b32 m0, s65
	ds_read_b128 v[150:153], v244 offset:22528
	ds_read_b128 v[178:181], v244 offset:23552
	buffer_load_dwordx4 v237, s[40:43], s93 offen lds
	s_waitcnt vmcnt(6)
	s_waitcnt lgkmcnt(0)
	s_barrier
	s_waitcnt lgkmcnt(0)
	v_mfma_f32_16x16x32_bf16 v[62:65], v[66:69], v[126:129], v[62:65]
	v_mfma_f32_16x16x32_bf16 v[62:65], v[70:73], v[130:133], v[62:65]
	v_mfma_f32_16x16x32_bf16 v[46:49], v[66:69], v[134:137], v[46:49]
	v_mfma_f32_16x16x32_bf16 v[46:49], v[70:73], v[138:141], v[46:49]
	v_mfma_f32_16x16x32_bf16 v[42:45], v[66:69], v[142:145], v[42:45]
	v_mfma_f32_16x16x32_bf16 v[42:45], v[70:73], v[146:149], v[42:45]
	v_mfma_f32_16x16x32_bf16 v[30:33], v[66:69], v[150:153], v[30:33]
	v_mfma_f32_16x16x32_bf16 v[30:33], v[70:73], v[178:181], v[30:33]
	v_mfma_f32_16x16x32_bf16 v[58:61], v[74:77], v[126:129], v[58:61]
	v_mfma_f32_16x16x32_bf16 v[58:61], v[78:81], v[130:133], v[58:61]
	v_mfma_f32_16x16x32_bf16 v[38:41], v[74:77], v[134:137], v[38:41]
	v_mfma_f32_16x16x32_bf16 v[38:41], v[78:81], v[138:141], v[38:41]
	v_mfma_f32_16x16x32_bf16 v[34:37], v[74:77], v[142:145], v[34:37]
	v_mfma_f32_16x16x32_bf16 v[34:37], v[78:81], v[146:149], v[34:37]
	v_mfma_f32_16x16x32_bf16 v[26:29], v[74:77], v[150:153], v[26:29]
	v_mfma_f32_16x16x32_bf16 v[26:29], v[78:81], v[178:181], v[26:29]
	v_mfma_f32_16x16x32_bf16 v[54:57], v[82:85], v[126:129], v[54:57]
	v_mfma_f32_16x16x32_bf16 v[54:57], v[86:89], v[130:133], v[54:57]
	v_mfma_f32_16x16x32_bf16 v[22:25], v[82:85], v[134:137], v[22:25]
	v_mfma_f32_16x16x32_bf16 v[22:25], v[86:89], v[138:141], v[22:25]
	v_mfma_f32_16x16x32_bf16 v[18:21], v[82:85], v[142:145], v[18:21]
	v_mfma_f32_16x16x32_bf16 v[18:21], v[86:89], v[146:149], v[18:21]
	v_mfma_f32_16x16x32_bf16 v[6:9], v[82:85], v[150:153], v[6:9]
	v_mfma_f32_16x16x32_bf16 v[6:9], v[86:89], v[178:181], v[6:9]
	v_mfma_f32_16x16x32_bf16 v[50:53], v[90:93], v[126:129], v[50:53]
	v_mfma_f32_16x16x32_bf16 v[50:53], v[94:97], v[130:133], v[50:53]
	v_mfma_f32_16x16x32_bf16 v[14:17], v[90:93], v[134:137], v[14:17]
	v_mfma_f32_16x16x32_bf16 v[14:17], v[94:97], v[138:141], v[14:17]
	v_mfma_f32_16x16x32_bf16 v[10:13], v[90:93], v[142:145], v[10:13]
	v_mfma_f32_16x16x32_bf16 v[10:13], v[94:97], v[146:149], v[10:13]
	v_mfma_f32_16x16x32_bf16 v[2:5], v[90:93], v[150:153], v[2:5]
	v_mfma_f32_16x16x32_bf16 v[2:5], v[94:97], v[178:181], v[2:5]
	s_barrier
	ds_read_b128 v[66:69], v245
	ds_read_b128 v[70:73], v245 offset:1024
	ds_read_b128 v[74:77], v245 offset:2048
	ds_read_b128 v[78:81], v245 offset:3072
	ds_read_b128 v[82:85], v246
	ds_read_b128 v[86:89], v246 offset:1024
	ds_read_b128 v[90:93], v246 offset:2048
	ds_read_b128 v[94:97], v246 offset:3072
	s_mov_b32 m0, s3
	ds_read_b128 v[126:129], v244 offset:32768
	ds_read_b128 v[130:133], v244 offset:33792
	buffer_load_dwordx4 v1, s[48:51], s92 offen lds
	s_mov_b32 m0, s70
	ds_read_b128 v[134:137], v244 offset:34816
	ds_read_b128 v[138:141], v244 offset:35840
	buffer_load_dwordx4 v236, s[48:51], s92 offen lds
	s_add_i32 s92, s92, 0x80000
	s_mov_b32 m0, s71
	ds_read_b128 v[194:197], v244 offset:36864
	ds_read_b128 v[198:201], v244 offset:37888
	buffer_load_dwordx4 v1, s[48:51], s92 offen lds
	s_mov_b32 m0, s72
	ds_read_b128 v[202:205], v244 offset:38912
	ds_read_b128 v[206:209], v244 offset:39936
	buffer_load_dwordx4 v236, s[48:51], s92 offen lds
	s_waitcnt vmcnt(8)
	s_waitcnt lgkmcnt(0)
	s_barrier
	s_waitcnt lgkmcnt(0)
	v_mfma_f32_16x16x32_bf16 v[142:145], v[66:69], v[126:129], v[190:193]
	v_mfma_f32_16x16x32_bf16 v[190:193], v[70:73], v[130:133], v[142:145]
	v_mfma_f32_16x16x32_bf16 v[142:145], v[74:77], v[126:129], v[186:189]
	v_mfma_f32_16x16x32_bf16 v[186:189], v[78:81], v[130:133], v[142:145]
	v_mfma_f32_16x16x32_bf16 v[142:145], v[66:69], v[134:137], v[174:177]
	v_mfma_f32_16x16x32_bf16 v[174:177], v[70:73], v[138:141], v[142:145]
	v_mfma_f32_16x16x32_bf16 v[142:145], v[74:77], v[134:137], v[166:169]
	v_mfma_f32_16x16x32_bf16 v[166:169], v[78:81], v[138:141], v[142:145]
	v_mfma_f32_16x16x32_bf16 v[142:145], v[66:69], v[194:197], v[170:173]
	v_mfma_f32_16x16x32_bf16 v[170:173], v[70:73], v[198:201], v[142:145]
	v_mfma_f32_16x16x32_bf16 v[142:145], v[74:77], v[194:197], v[162:165]
	v_mfma_f32_16x16x32_bf16 v[162:165], v[78:81], v[198:201], v[142:145]
	v_mfma_f32_16x16x32_bf16 v[142:145], v[66:69], v[202:205], v[158:161]
	v_mfma_f32_16x16x32_bf16 v[158:161], v[70:73], v[206:209], v[142:145]
	v_mfma_f32_16x16x32_bf16 v[142:145], v[74:77], v[202:205], v[154:157]
	v_mfma_f32_16x16x32_bf16 v[154:157], v[78:81], v[206:209], v[142:145]
	v_mfma_f32_16x16x32_bf16 v[98:101], v[90:93], v[126:129], v[98:101]
	v_mfma_f32_16x16x32_bf16 v[178:181], v[94:97], v[130:133], v[98:101]
	v_mfma_f32_16x16x32_bf16 v[98:101], v[82:85], v[134:137], v[102:105]
	v_mfma_f32_16x16x32_bf16 v[150:153], v[86:89], v[138:141], v[98:101]
	v_mfma_f32_16x16x32_bf16 v[98:101], v[90:93], v[134:137], v[106:109]
	v_mfma_f32_16x16x32_bf16 v[142:145], v[82:85], v[126:129], v[182:185]
	v_mfma_f32_16x16x32_bf16 v[182:185], v[86:89], v[130:133], v[142:145]
	v_mfma_f32_16x16x32_bf16 v[142:145], v[94:97], v[138:141], v[98:101]
	v_mfma_f32_16x16x32_bf16 v[98:101], v[82:85], v[194:197], v[110:113]
	v_mfma_f32_16x16x32_bf16 v[146:149], v[86:89], v[198:201], v[98:101]
	v_mfma_f32_16x16x32_bf16 v[98:101], v[90:93], v[194:197], v[114:117]
	v_mfma_f32_16x16x32_bf16 v[138:141], v[94:97], v[198:201], v[98:101]
	v_mfma_f32_16x16x32_bf16 v[98:101], v[82:85], v[202:205], v[118:121]
	v_mfma_f32_16x16x32_bf16 v[134:137], v[86:89], v[206:209], v[98:101]
	v_mfma_f32_16x16x32_bf16 v[98:101], v[90:93], v[202:205], v[122:125]
	v_mfma_f32_16x16x32_bf16 v[130:133], v[94:97], v[206:209], v[98:101]
	s_barrier
	s_mov_b32 m0, s74
	s_or_b32 s92, s91, 0x80
	s_nop 2
	ds_read_b128 v[98:101], v244 offset:49152
	ds_read_b128 v[102:105], v244 offset:50176
	buffer_load_dwordx4 v227, s[40:43], s92 offen lds
	s_mov_b32 m0, s75
	ds_read_b128 v[106:109], v244 offset:51200
	ds_read_b128 v[110:113], v244 offset:52224
	buffer_load_dwordx4 v237, s[40:43], s92 offen lds
	s_add_i32 s91, s91, 0x1600080
	s_mov_b32 m0, s77
	ds_read_b128 v[114:117], v244 offset:53248
	ds_read_b128 v[118:121], v244 offset:54272
	buffer_load_dwordx4 v227, s[40:43], s91 offen lds
	s_mov_b32 m0, s78
	ds_read_b128 v[122:125], v244 offset:55296
	ds_read_b128 v[126:129], v244 offset:56320
	buffer_load_dwordx4 v237, s[40:43], s91 offen lds
	s_waitcnt vmcnt(6)
	s_waitcnt lgkmcnt(0)
	s_barrier
	s_waitcnt lgkmcnt(0)
	v_mfma_f32_16x16x32_bf16 v[62:65], v[66:69], v[98:101], v[62:65]
	v_mfma_f32_16x16x32_bf16 v[62:65], v[70:73], v[102:105], v[62:65]
	v_mfma_f32_16x16x32_bf16 v[46:49], v[66:69], v[106:109], v[46:49]
	v_mfma_f32_16x16x32_bf16 v[46:49], v[70:73], v[110:113], v[46:49]
	v_mfma_f32_16x16x32_bf16 v[42:45], v[66:69], v[114:117], v[42:45]
	v_mfma_f32_16x16x32_bf16 v[42:45], v[70:73], v[118:121], v[42:45]
	v_mfma_f32_16x16x32_bf16 v[30:33], v[66:69], v[122:125], v[30:33]
	v_mfma_f32_16x16x32_bf16 v[30:33], v[70:73], v[126:129], v[30:33]
	v_mfma_f32_16x16x32_bf16 v[58:61], v[74:77], v[98:101], v[58:61]
	v_mfma_f32_16x16x32_bf16 v[58:61], v[78:81], v[102:105], v[58:61]
	v_mfma_f32_16x16x32_bf16 v[38:41], v[74:77], v[106:109], v[38:41]
	v_mfma_f32_16x16x32_bf16 v[38:41], v[78:81], v[110:113], v[38:41]
	v_mfma_f32_16x16x32_bf16 v[34:37], v[74:77], v[114:117], v[34:37]
	v_mfma_f32_16x16x32_bf16 v[34:37], v[78:81], v[118:121], v[34:37]
	v_mfma_f32_16x16x32_bf16 v[26:29], v[74:77], v[122:125], v[26:29]
	v_mfma_f32_16x16x32_bf16 v[26:29], v[78:81], v[126:129], v[26:29]
	v_mfma_f32_16x16x32_bf16 v[54:57], v[82:85], v[98:101], v[54:57]
	v_mfma_f32_16x16x32_bf16 v[54:57], v[86:89], v[102:105], v[54:57]
	v_mfma_f32_16x16x32_bf16 v[22:25], v[82:85], v[106:109], v[22:25]
	v_mfma_f32_16x16x32_bf16 v[22:25], v[86:89], v[110:113], v[22:25]
	v_mfma_f32_16x16x32_bf16 v[18:21], v[82:85], v[114:117], v[18:21]
	v_mfma_f32_16x16x32_bf16 v[18:21], v[86:89], v[118:121], v[18:21]
	v_mfma_f32_16x16x32_bf16 v[6:9], v[82:85], v[122:125], v[6:9]
	v_mfma_f32_16x16x32_bf16 v[6:9], v[86:89], v[126:129], v[6:9]
	v_mfma_f32_16x16x32_bf16 v[50:53], v[90:93], v[98:101], v[50:53]
	v_mfma_f32_16x16x32_bf16 v[50:53], v[94:97], v[102:105], v[50:53]
	v_mfma_f32_16x16x32_bf16 v[14:17], v[90:93], v[106:109], v[14:17]
	v_mfma_f32_16x16x32_bf16 v[14:17], v[94:97], v[110:113], v[14:17]
	v_mfma_f32_16x16x32_bf16 v[10:13], v[90:93], v[114:117], v[10:13]
	v_mfma_f32_16x16x32_bf16 v[10:13], v[94:97], v[118:121], v[10:13]
	v_mfma_f32_16x16x32_bf16 v[2:5], v[90:93], v[122:125], v[2:5]
	v_mfma_f32_16x16x32_bf16 v[2:5], v[94:97], v[126:129], v[2:5]
	s_barrier
	s_add_i32 s69, s69, 2
	s_addk_i32 s67, 0x100
	s_addk_i32 s68, 0x100
	s_cmp_gt_u32 s69, 29
	s_cbranch_scc0 .LBB0_822
	s_and_b64 vcc, exec, s[38:39]
	s_cbranch_vccz .LBB0_825
	s_barrier

.LBB0_1003:
	v_add_u32_e32 v130, 0x10000, v155
	ds_read_b128 v[132:135], v130
	ds_read_b128 v[144:147], v130 offset:1024
	ds_read_b128 v[158:161], v130 offset:2048
	ds_read_b128 v[162:165], v130 offset:3072
	v_add_u32_e32 v130, 0x14000, v155
	s_lshl_b32 s39, s92, 7
	ds_read_b128 v[166:169], v130
	ds_read_b128 v[170:173], v130 offset:1024
	ds_read_b128 v[174:177], v130 offset:2048
	ds_read_b128 v[178:181], v130 offset:3072
	s_add_i32 s93, s61, s39
	s_addk_i32 s39, 0x100
	s_add_i32 s94, s93, 0x80
	s_add_i32 s95, s39, s61
	s_and_b64 s[50:51], s[48:49], exec
	s_cselect_b32 s50, s87, s95
	s_add_i32 s39, s39, s63
	s_and_b64 s[48:49], s[48:49], exec
	s_cselect_b32 s48, s88, s39
	s_or_b32 s49, s48, 0x80
	s_mov_b32 m0, s77
	ds_read_b128 v[182:185], v156
	ds_read_b128 v[186:189], v156 offset:1024
	buffer_load_dwordx4 v151, s[28:31], s94 offen lds
	s_mov_b32 m0, s78
	ds_read_b128 v[190:193], v156 offset:2048
	ds_read_b128 v[194:197], v156 offset:3072
	buffer_load_dwordx4 v153, s[28:31], s94 offen lds
	s_add_i32 s93, s93, 0x160080
	s_mov_b32 m0, s79
	ds_read_b128 v[198:201], v156 offset:4096
	ds_read_b128 v[202:205], v156 offset:5120
	buffer_load_dwordx4 v151, s[28:31], s93 offen lds
	s_mov_b32 m0, s80
	ds_read_b128 v[206:209], v156 offset:6144
	ds_read_b128 v[210:213], v156 offset:7168
	buffer_load_dwordx4 v153, s[28:31], s93 offen lds
	s_waitcnt vmcnt(8)
	s_waitcnt lgkmcnt(0)
	s_barrier
	s_waitcnt lgkmcnt(0)
	v_mfma_f32_16x16x32_bf16 v[126:129], v[132:135], v[182:185], v[126:129]
	v_mfma_f32_16x16x32_bf16 v[126:129], v[144:147], v[186:189], v[126:129]
	v_mfma_f32_16x16x32_bf16 v[110:113], v[132:135], v[190:193], v[110:113]
	v_mfma_f32_16x16x32_bf16 v[110:113], v[144:147], v[194:197], v[110:113]
	v_mfma_f32_16x16x32_bf16 v[94:97], v[132:135], v[198:201], v[94:97]
	v_mfma_f32_16x16x32_bf16 v[94:97], v[144:147], v[202:205], v[94:97]
	v_mfma_f32_16x16x32_bf16 v[78:81], v[132:135], v[206:209], v[78:81]
	v_mfma_f32_16x16x32_bf16 v[78:81], v[144:147], v[210:213], v[78:81]
	v_mfma_f32_16x16x32_bf16 v[122:125], v[158:161], v[182:185], v[122:125]
	v_mfma_f32_16x16x32_bf16 v[122:125], v[162:165], v[186:189], v[122:125]
	v_mfma_f32_16x16x32_bf16 v[106:109], v[158:161], v[190:193], v[106:109]
	v_mfma_f32_16x16x32_bf16 v[106:109], v[162:165], v[194:197], v[106:109]
	v_mfma_f32_16x16x32_bf16 v[90:93], v[158:161], v[198:201], v[90:93]
	v_mfma_f32_16x16x32_bf16 v[90:93], v[162:165], v[202:205], v[90:93]
	v_mfma_f32_16x16x32_bf16 v[74:77], v[158:161], v[206:209], v[74:77]
	v_mfma_f32_16x16x32_bf16 v[74:77], v[162:165], v[210:213], v[74:77]
	v_mfma_f32_16x16x32_bf16 v[118:121], v[166:169], v[182:185], v[118:121]
	v_mfma_f32_16x16x32_bf16 v[118:121], v[170:173], v[186:189], v[118:121]
	v_mfma_f32_16x16x32_bf16 v[102:105], v[166:169], v[190:193], v[102:105]
	v_mfma_f32_16x16x32_bf16 v[102:105], v[170:173], v[194:197], v[102:105]
	v_mfma_f32_16x16x32_bf16 v[86:89], v[166:169], v[198:201], v[86:89]
	v_mfma_f32_16x16x32_bf16 v[86:89], v[170:173], v[202:205], v[86:89]
	v_mfma_f32_16x16x32_bf16 v[70:73], v[166:169], v[206:209], v[70:73]
	v_mfma_f32_16x16x32_bf16 v[70:73], v[170:173], v[210:213], v[70:73]
	v_mfma_f32_16x16x32_bf16 v[114:117], v[174:177], v[182:185], v[114:117]
	v_mfma_f32_16x16x32_bf16 v[114:117], v[178:181], v[186:189], v[114:117]
	v_mfma_f32_16x16x32_bf16 v[98:101], v[174:177], v[190:193], v[98:101]
	v_mfma_f32_16x16x32_bf16 v[98:101], v[178:181], v[194:197], v[98:101]
	v_mfma_f32_16x16x32_bf16 v[82:85], v[174:177], v[198:201], v[82:85]
	v_mfma_f32_16x16x32_bf16 v[82:85], v[178:181], v[202:205], v[82:85]
	v_mfma_f32_16x16x32_bf16 v[66:69], v[174:177], v[206:209], v[66:69]
	v_mfma_f32_16x16x32_bf16 v[66:69], v[178:181], v[210:213], v[66:69]
	s_barrier
	s_mov_b32 m0, s64
	s_mov_b32 s39, s31
	ds_read_b128 v[182:185], v156 offset:16384
	ds_read_b128 v[186:189], v156 offset:17408
	buffer_load_dwordx4 v152, s[36:39], s48 offen lds
	s_mov_b32 m0, s65
	ds_read_b128 v[190:193], v156 offset:18432
	ds_read_b128 v[194:197], v156 offset:19456
	buffer_load_dwordx4 v154, s[36:39], s48 offen lds
	s_add_i32 s51, s48, 0x160000
	s_mov_b32 m0, s66
	ds_read_b128 v[198:201], v156 offset:20480
	ds_read_b128 v[202:205], v156 offset:21504
	buffer_load_dwordx4 v152, s[36:39], s51 offen lds
	s_mov_b32 m0, s67
	ds_read_b128 v[206:209], v156 offset:22528
	ds_read_b128 v[210:213], v156 offset:23552
	buffer_load_dwordx4 v154, s[36:39], s51 offen lds
	s_waitcnt vmcnt(6)
	s_waitcnt lgkmcnt(0)
	s_barrier
	s_waitcnt lgkmcnt(0)
	v_mfma_f32_16x16x32_bf16 v[62:65], v[132:135], v[182:185], v[62:65]
	v_mfma_f32_16x16x32_bf16 v[62:65], v[144:147], v[186:189], v[62:65]
	v_mfma_f32_16x16x32_bf16 v[46:49], v[132:135], v[190:193], v[46:49]
	v_mfma_f32_16x16x32_bf16 v[46:49], v[144:147], v[194:197], v[46:49]
	v_mfma_f32_16x16x32_bf16 v[30:33], v[132:135], v[198:201], v[30:33]
	v_mfma_f32_16x16x32_bf16 v[30:33], v[144:147], v[202:205], v[30:33]
	v_mfma_f32_16x16x32_bf16 v[14:17], v[132:135], v[206:209], v[14:17]
	v_mfma_f32_16x16x32_bf16 v[14:17], v[144:147], v[210:213], v[14:17]
	v_mfma_f32_16x16x32_bf16 v[58:61], v[158:161], v[182:185], v[58:61]
	v_mfma_f32_16x16x32_bf16 v[58:61], v[162:165], v[186:189], v[58:61]
	v_mfma_f32_16x16x32_bf16 v[42:45], v[158:161], v[190:193], v[42:45]
	v_mfma_f32_16x16x32_bf16 v[42:45], v[162:165], v[194:197], v[42:45]
	v_mfma_f32_16x16x32_bf16 v[26:29], v[158:161], v[198:201], v[26:29]
	v_mfma_f32_16x16x32_bf16 v[26:29], v[162:165], v[202:205], v[26:29]
	v_mfma_f32_16x16x32_bf16 v[10:13], v[158:161], v[206:209], v[10:13]
	v_mfma_f32_16x16x32_bf16 v[10:13], v[162:165], v[210:213], v[10:13]
	v_mfma_f32_16x16x32_bf16 v[54:57], v[166:169], v[182:185], v[54:57]
	v_mfma_f32_16x16x32_bf16 v[54:57], v[170:173], v[186:189], v[54:57]
	v_mfma_f32_16x16x32_bf16 v[38:41], v[166:169], v[190:193], v[38:41]
	v_mfma_f32_16x16x32_bf16 v[38:41], v[170:173], v[194:197], v[38:41]
	v_mfma_f32_16x16x32_bf16 v[22:25], v[166:169], v[198:201], v[22:25]
	v_mfma_f32_16x16x32_bf16 v[22:25], v[170:173], v[202:205], v[22:25]
	v_mfma_f32_16x16x32_bf16 v[6:9], v[166:169], v[206:209], v[6:9]
	v_mfma_f32_16x16x32_bf16 v[6:9], v[170:173], v[210:213], v[6:9]
	v_mfma_f32_16x16x32_bf16 v[50:53], v[174:177], v[182:185], v[50:53]
	v_mfma_f32_16x16x32_bf16 v[50:53], v[178:181], v[186:189], v[50:53]
	v_mfma_f32_16x16x32_bf16 v[34:37], v[174:177], v[190:193], v[34:37]
	v_mfma_f32_16x16x32_bf16 v[34:37], v[178:181], v[194:197], v[34:37]
	v_mfma_f32_16x16x32_bf16 v[18:21], v[174:177], v[198:201], v[18:21]
	v_mfma_f32_16x16x32_bf16 v[18:21], v[178:181], v[202:205], v[18:21]
	v_mfma_f32_16x16x32_bf16 v[2:5], v[174:177], v[206:209], v[2:5]
	v_mfma_f32_16x16x32_bf16 v[2:5], v[178:181], v[210:213], v[2:5]
	s_barrier
	v_add_u32_e32 v130, 0x18000, v155
	ds_read_b128 v[132:135], v130
	ds_read_b128 v[144:147], v130 offset:1024
	ds_read_b128 v[158:161], v130 offset:2048
	ds_read_b128 v[162:165], v130 offset:3072
	v_add_u32_e32 v130, 0x1c000, v155
	ds_read_b128 v[166:169], v130
	ds_read_b128 v[170:173], v130 offset:1024
	ds_read_b128 v[174:177], v130 offset:2048
	ds_read_b128 v[178:181], v130 offset:3072
	s_mov_b32 m0, s62
	ds_read_b128 v[182:185], v156 offset:32768
	ds_read_b128 v[186:189], v156 offset:33792
	buffer_load_dwordx4 v151, s[28:31], s50 offen lds
	s_mov_b32 m0, s68
	ds_read_b128 v[190:193], v156 offset:34816
	ds_read_b128 v[194:197], v156 offset:35840
	buffer_load_dwordx4 v153, s[28:31], s50 offen lds
	s_add_i32 s50, s50, 0x160000
	s_mov_b32 m0, s69
	ds_read_b128 v[198:201], v156 offset:36864
	ds_read_b128 v[202:205], v156 offset:37888
	buffer_load_dwordx4 v151, s[28:31], s50 offen lds
	s_mov_b32 m0, s70
	ds_read_b128 v[206:209], v156 offset:38912
	ds_read_b128 v[210:213], v156 offset:39936
	buffer_load_dwordx4 v153, s[28:31], s50 offen lds
	s_waitcnt vmcnt(8)
	s_waitcnt lgkmcnt(0)
	s_barrier
	s_waitcnt lgkmcnt(0)
	v_mfma_f32_16x16x32_bf16 v[126:129], v[132:135], v[182:185], v[126:129]
	v_mfma_f32_16x16x32_bf16 v[126:129], v[144:147], v[186:189], v[126:129]
	v_mfma_f32_16x16x32_bf16 v[110:113], v[132:135], v[190:193], v[110:113]
	v_mfma_f32_16x16x32_bf16 v[110:113], v[144:147], v[194:197], v[110:113]
	v_mfma_f32_16x16x32_bf16 v[94:97], v[132:135], v[198:201], v[94:97]
	v_mfma_f32_16x16x32_bf16 v[94:97], v[144:147], v[202:205], v[94:97]
	v_mfma_f32_16x16x32_bf16 v[78:81], v[132:135], v[206:209], v[78:81]
	v_mfma_f32_16x16x32_bf16 v[78:81], v[144:147], v[210:213], v[78:81]
	v_mfma_f32_16x16x32_bf16 v[122:125], v[158:161], v[182:185], v[122:125]
	v_mfma_f32_16x16x32_bf16 v[122:125], v[162:165], v[186:189], v[122:125]
	v_mfma_f32_16x16x32_bf16 v[106:109], v[158:161], v[190:193], v[106:109]
	v_mfma_f32_16x16x32_bf16 v[106:109], v[162:165], v[194:197], v[106:109]
	v_mfma_f32_16x16x32_bf16 v[90:93], v[158:161], v[198:201], v[90:93]
	v_mfma_f32_16x16x32_bf16 v[90:93], v[162:165], v[202:205], v[90:93]
	v_mfma_f32_16x16x32_bf16 v[74:77], v[158:161], v[206:209], v[74:77]
	v_mfma_f32_16x16x32_bf16 v[74:77], v[162:165], v[210:213], v[74:77]
	v_mfma_f32_16x16x32_bf16 v[118:121], v[166:169], v[182:185], v[118:121]
	v_mfma_f32_16x16x32_bf16 v[118:121], v[170:173], v[186:189], v[118:121]
	v_mfma_f32_16x16x32_bf16 v[102:105], v[166:169], v[190:193], v[102:105]
	v_mfma_f32_16x16x32_bf16 v[102:105], v[170:173], v[194:197], v[102:105]
	v_mfma_f32_16x16x32_bf16 v[86:89], v[166:169], v[198:201], v[86:89]
	v_mfma_f32_16x16x32_bf16 v[86:89], v[170:173], v[202:205], v[86:89]
	v_mfma_f32_16x16x32_bf16 v[70:73], v[166:169], v[206:209], v[70:73]
	v_mfma_f32_16x16x32_bf16 v[70:73], v[170:173], v[210:213], v[70:73]
	v_mfma_f32_16x16x32_bf16 v[114:117], v[174:177], v[182:185], v[114:117]
	v_mfma_f32_16x16x32_bf16 v[114:117], v[178:181], v[186:189], v[114:117]
	v_mfma_f32_16x16x32_bf16 v[98:101], v[174:177], v[190:193], v[98:101]
	v_mfma_f32_16x16x32_bf16 v[98:101], v[178:181], v[194:197], v[98:101]
	v_mfma_f32_16x16x32_bf16 v[82:85], v[174:177], v[198:201], v[82:85]
	v_mfma_f32_16x16x32_bf16 v[82:85], v[178:181], v[202:205], v[82:85]
	v_mfma_f32_16x16x32_bf16 v[66:69], v[174:177], v[206:209], v[66:69]
	v_mfma_f32_16x16x32_bf16 v[66:69], v[178:181], v[210:213], v[66:69]
	s_barrier
	s_mov_b32 m0, s72
	ds_read_b128 v[182:185], v156 offset:49152
	ds_read_b128 v[186:189], v156 offset:50176
	buffer_load_dwordx4 v152, s[36:39], s49 offen lds
	s_mov_b32 m0, s73
	ds_read_b128 v[190:193], v156 offset:51200
	ds_read_b128 v[194:197], v156 offset:52224
	buffer_load_dwordx4 v154, s[36:39], s49 offen lds
	s_add_i32 s48, s48, 0x160080
	s_mov_b32 m0, s74
	ds_read_b128 v[198:201], v156 offset:53248
	ds_read_b128 v[202:205], v156 offset:54272
	buffer_load_dwordx4 v152, s[36:39], s48 offen lds
	s_mov_b32 m0, s75
	ds_read_b128 v[206:209], v156 offset:55296
	ds_read_b128 v[210:213], v156 offset:56320
	buffer_load_dwordx4 v154, s[36:39], s48 offen lds
	s_waitcnt vmcnt(6)
	s_waitcnt lgkmcnt(0)
	s_barrier
	s_waitcnt lgkmcnt(0)
	v_mfma_f32_16x16x32_bf16 v[62:65], v[132:135], v[182:185], v[62:65]
	v_mfma_f32_16x16x32_bf16 v[62:65], v[144:147], v[186:189], v[62:65]
	v_mfma_f32_16x16x32_bf16 v[46:49], v[132:135], v[190:193], v[46:49]
	v_mfma_f32_16x16x32_bf16 v[46:49], v[144:147], v[194:197], v[46:49]
	v_mfma_f32_16x16x32_bf16 v[30:33], v[132:135], v[198:201], v[30:33]
	v_mfma_f32_16x16x32_bf16 v[30:33], v[144:147], v[202:205], v[30:33]
	v_mfma_f32_16x16x32_bf16 v[14:17], v[132:135], v[206:209], v[14:17]
	v_mfma_f32_16x16x32_bf16 v[14:17], v[144:147], v[210:213], v[14:17]
	v_mfma_f32_16x16x32_bf16 v[58:61], v[158:161], v[182:185], v[58:61]
	v_mfma_f32_16x16x32_bf16 v[58:61], v[162:165], v[186:189], v[58:61]
	v_mfma_f32_16x16x32_bf16 v[42:45], v[158:161], v[190:193], v[42:45]
	v_mfma_f32_16x16x32_bf16 v[42:45], v[162:165], v[194:197], v[42:45]
	v_mfma_f32_16x16x32_bf16 v[26:29], v[158:161], v[198:201], v[26:29]
	v_mfma_f32_16x16x32_bf16 v[26:29], v[162:165], v[202:205], v[26:29]
	v_mfma_f32_16x16x32_bf16 v[10:13], v[158:161], v[206:209], v[10:13]
	v_mfma_f32_16x16x32_bf16 v[10:13], v[162:165], v[210:213], v[10:13]
	v_mfma_f32_16x16x32_bf16 v[54:57], v[166:169], v[182:185], v[54:57]
	v_mfma_f32_16x16x32_bf16 v[54:57], v[170:173], v[186:189], v[54:57]
	v_mfma_f32_16x16x32_bf16 v[38:41], v[166:169], v[190:193], v[38:41]
	v_mfma_f32_16x16x32_bf16 v[38:41], v[170:173], v[194:197], v[38:41]
	v_mfma_f32_16x16x32_bf16 v[22:25], v[166:169], v[198:201], v[22:25]
	v_mfma_f32_16x16x32_bf16 v[22:25], v[170:173], v[202:205], v[22:25]
	v_mfma_f32_16x16x32_bf16 v[6:9], v[166:169], v[206:209], v[6:9]
	v_mfma_f32_16x16x32_bf16 v[6:9], v[170:173], v[210:213], v[6:9]
	v_mfma_f32_16x16x32_bf16 v[50:53], v[174:177], v[182:185], v[50:53]
	v_mfma_f32_16x16x32_bf16 v[50:53], v[178:181], v[186:189], v[50:53]
	v_mfma_f32_16x16x32_bf16 v[34:37], v[174:177], v[190:193], v[34:37]
	v_mfma_f32_16x16x32_bf16 v[34:37], v[178:181], v[194:197], v[34:37]
	v_mfma_f32_16x16x32_bf16 v[18:21], v[174:177], v[198:201], v[18:21]
	v_mfma_f32_16x16x32_bf16 v[18:21], v[178:181], v[202:205], v[18:21]
	v_mfma_f32_16x16x32_bf16 v[2:5], v[174:177], v[206:209], v[2:5]
	v_mfma_f32_16x16x32_bf16 v[2:5], v[178:181], v[210:213], v[2:5]
	s_barrier
	s_add_i32 s39, s92, 2
	s_cmpk_gt_u32 s92, 0x55
	s_cbranch_scc1 .LBB0_1005
	s_mov_b32 s92, s39
	s_branch .LBB0_999
